# o4+o8 plus static s_setprio 1 for waves 4-7 around the four gemm256 K-loops
# speedup vs baseline: 1.0389x; 1.0020x over previous
; #define LAS __attribute__((address_space(3)))
; #define GLDS_STAGE(st, kt_) do { \
;         _Pragma("unroll") for (int i_ = 0; i_ < FI; ++i_) { \
;             glds16(ap + (size_t)(32 * i_) * lda + (kt_) * 64, l3a + (st) + tid * 16 + i_ * 4096); \
;             glds16(bp + (size_t)(32 * i_) * ldb + (kt_) * 64, l3a + (st) + OPB + tid * 16 + i_ * 4096); } } while (0)
; #define GLDS_STAGE(st, kt_) do { \
;         _Pragma("unroll") for (int i_ = 0; i_ < 4; ++i_) { \
;             glds16(ap + (size_t)(64 * i_) * lda + (kt_) * 64, l3a + (st) + tid * 16 + i_ * 8192); \
;             glds16(bp + (size_t)(64 * i_) * ldb + (kt_) * 64, l3a + (st) + 32768 + tid * 16 + i_ * 8192); } } while (0)
; template <class Epi>
; DEV void gemm256_tile(const bf16_t* __restrict__ A, int lda, const bf16_t* __restrict__ Bt, int ldb, int K, unsigned char* lds, const Epi& epi) {
;     int tid = threadIdx.x; asm volatile("" : "+v"(tid)); const int lane = tid & 63, wid = tid >> 6;
;     const int wr = wid >> 2, wc = wid & 3, fr = lane & 15, fq = lane >> 4;
;     f32x4 acc[8][4];
; #pragma unroll
;     for (int i = 0; i < 8; ++i)
; #pragma unroll
;         for (int j = 0; j < 4; ++j) acc[i][j] = (f32x4){0.f, 0.f, 0.f, 0.f};
;     const int lrow = tid >> 3, lcs = (tid & 7) ^ (lrow & 7);
;     const bf16_t* ap = A + (size_t)lrow * lda + lcs * 8;
;     const bf16_t* bp = Bt + (size_t)lrow * ldb + lcs * 8;
;     const unsigned l3a = (unsigned)(size_t)(LAS unsigned char*)lds;
;     const int nk = K >> 6;
;     ...
;     GLDS_STAGE(0, 0);
;     const int aoff = (wr * 128 + fr) * 128, boff = 32768 + (wc * 64 + fr) * 128, sw = fr & 7;
.LBB0_173:
	s_and_b32 s19, s18, 7
	s_mulk_i32 s19, 0x60
	s_ashr_i32 s20, s18, 3
	s_add_i32 s19, s19, s20
	s_mul_hi_i32 s20, s19, 0x2aaaaaab
	s_lshr_b32 s21, s20, 31
	s_ashr_i32 s20, s20, 5
	s_add_i32 s20, s20, s21
	s_lshl_b32 s21, s20, 3
	s_mulk_i32 s20, 0xc0
	s_sub_i32 s19, s19, s20
	s_sext_i32_i16 s20, s19
	s_bfe_u32 s20, s20, 0x3001c
	s_add_i32 s22, s19, s20
	s_sext_i32_i16 s24, s22
	s_and_b32 s22, s22, 0xfff8
	s_sub_i32 s19, s19, s22
	v_mov_b32_e32 v150, v0
	s_sext_i32_i16 s19, s19
	s_add_i32 s19, s21, s19
	v_ashrrev_i32_e32 v10, 3, v150
	s_ashr_i32 s21, s24, 3
	v_xor_b32_e32 v8, v10, v150
	v_mad_i64_i32 v[2:3], s[22:23], s19, v148, v[166:167]
	v_mad_i64_i32 v[4:5], s[22:23], s21, v148, v[130:131]
	v_lshlrev_b32_e32 v8, 4, v8
	v_mad_i64_i32 v[2:3], s[22:23], v10, s13, v[2:3]
	v_and_b32_e32 v142, 0x70, v8
	v_mad_i64_i32 v[4:5], s[22:23], v10, s13, v[4:5]
	v_mad_i64_i32 v[6:7], s[22:23], v10, s13, 0
	v_lshl_add_u64 v[2:3], v[2:3], 0, v[142:143]
	v_lshl_add_u64 v[4:5], v[4:5], 0, v[142:143]
	v_lshlrev_b32_e32 v142, 4, v150
	v_add_u32_e32 v156, 0x8000, v142
	v_readfirstlane_b32 s22, v142
	s_mov_b32 s23, m0
	s_mov_b32 m0, s22
	s_nop 0
	global_load_lds_dwordx4 v[2:3], off
	s_mov_b32 m0, s23
	s_lshr_b32 s20, s24, 3
	v_readfirstlane_b32 s23, v156
	s_mov_b32 s24, m0
	s_mov_b32 m0, s23
	s_nop 0
	global_load_lds_dwordx4 v[4:5], off
	s_mov_b32 m0, s24
	v_lshl_add_u64 v[8:9], v[2:3], 0, s[4:5]
	s_add_i32 s23, s22, 0x2000
	s_mov_b32 s24, m0
	s_mov_b32 m0, s23
	s_nop 0
	global_load_lds_dwordx4 v[8:9], off
	s_mov_b32 m0, s24
	v_lshl_add_u64 v[8:9], v[4:5], 0, s[4:5]
	s_add_i32 s23, s22, 0xa000
	s_mov_b32 s24, m0
	s_mov_b32 m0, s23
	s_nop 0
	global_load_lds_dwordx4 v[8:9], off
	s_mov_b32 m0, s24
	v_lshl_add_u64 v[8:9], v[2:3], 0, s[6:7]
	s_add_i32 s23, s22, 0x4000
	s_mov_b32 s24, m0
	s_mov_b32 m0, s23
	s_nop 0
	global_load_lds_dwordx4 v[8:9], off
	s_mov_b32 m0, s24
	v_lshl_add_u64 v[8:9], v[4:5], 0, s[6:7]
	s_add_i32 s23, s22, 0xc000
	s_mov_b32 s24, m0
	s_mov_b32 m0, s23
	s_nop 0
	global_load_lds_dwordx4 v[8:9], off
	s_mov_b32 m0, s24
	v_lshl_add_u64 v[2:3], v[2:3], 0, s[8:9]
	s_add_i32 s23, s22, 0x6000
	s_mov_b32 s24, m0
	s_mov_b32 m0, s23
	s_nop 0
	global_load_lds_dwordx4 v[2:3], off
	s_mov_b32 m0, s24
	v_lshl_add_u64 v[2:3], v[4:5], 0, s[8:9]
	v_and_b32_e32 v151, 15, v150
	s_add_i32 s22, s22, 0xe000
	s_mov_b32 s23, m0
	s_mov_b32 m0, s22
	s_nop 0
	global_load_lds_dwordx4 v[2:3], off
	s_mov_b32 m0, s23
	v_ashrrev_i32_e32 v2, 1, v150
	v_and_or_b32 v154, v2, s16, v151
	v_lshlrev_b32_e32 v2, 7, v150
	v_lshrrev_b32_e32 v152, 4, v150
	v_bfe_u32 v153, v150, 4, 2
	v_and_b32_e32 v175, 0x6780, v2
	v_and_b32_e32 v2, 7, v150
	v_bitop3_b32 v3, v152, v2, 3 bitop3:0x6c
	v_bitop3_b32 v2, v153, v2, 4 bitop3:0x36
	v_bitop3_b32 v4, v10, 7, v150 bitop3:0x48
	v_lshlrev_b32_e32 v174, 4, v3
	v_lshlrev_b32_e32 v155, 4, v2
	v_mad_i64_i32 v[2:3], s[22:23], s19, v148, v[6:7]
	v_lshlrev_b32_e32 v4, 4, v4
	v_or_b32_e32 v2, v2, v4
	v_lshl_add_u64 v[144:145], v[136:137], 0, v[2:3]
	v_mad_i64_i32 v[2:3], s[22:23], s21, v148, v[6:7]
	v_or_b32_e32 v2, v2, v4
	v_lshlrev_b32_e32 v157, 7, v154
	v_lshl_add_u64 v[146:147], v[140:141], 0, v[2:3]
	s_mov_b32 s21, 0
	v_mov_b32_e32 v38, v143
	v_mov_b32_e32 v39, v143
	v_mov_b32_e32 v40, v143
	v_mov_b32_e32 v41, v143
	v_mov_b32_e32 v2, v143
	v_mov_b32_e32 v3, v143
	v_mov_b32_e32 v4, v143
	v_mov_b32_e32 v5, v143
	v_mov_b32_e32 v6, v143
	v_mov_b32_e32 v7, v143
	v_mov_b32_e32 v8, v143
	v_mov_b32_e32 v9, v143
	v_mov_b32_e32 v10, v143
	v_mov_b32_e32 v11, v143
	v_mov_b32_e32 v12, v143
	v_mov_b32_e32 v13, v143
	v_mov_b32_e32 v14, v143
	v_mov_b32_e32 v15, v143
	v_mov_b32_e32 v16, v143
	v_mov_b32_e32 v17, v143
	v_mov_b32_e32 v18, v143
	v_mov_b32_e32 v19, v143
	v_mov_b32_e32 v20, v143
	v_mov_b32_e32 v21, v143
	v_mov_b32_e32 v22, v143
	v_mov_b32_e32 v23, v143
	v_mov_b32_e32 v24, v143
	v_mov_b32_e32 v25, v143
	v_mov_b32_e32 v26, v143
	v_mov_b32_e32 v27, v143
	v_mov_b32_e32 v28, v143
	v_mov_b32_e32 v29, v143
	v_mov_b32_e32 v30, v143
	v_mov_b32_e32 v31, v143
	v_mov_b32_e32 v32, v143
	v_mov_b32_e32 v33, v143
	v_mov_b32_e32 v34, v143
	v_mov_b32_e32 v35, v143
	v_mov_b32_e32 v36, v143
	v_mov_b32_e32 v37, v143
	v_mov_b32_e32 v42, v143
	v_mov_b32_e32 v43, v143
	v_mov_b32_e32 v44, v143
	v_mov_b32_e32 v45, v143
	v_mov_b32_e32 v46, v143
	v_mov_b32_e32 v47, v143
	v_mov_b32_e32 v48, v143
	v_mov_b32_e32 v49, v143
	v_mov_b32_e32 v50, v143
	v_mov_b32_e32 v51, v143
	v_mov_b32_e32 v52, v143
	v_mov_b32_e32 v53, v143
	v_mov_b32_e32 v54, v143
	v_mov_b32_e32 v55, v143
	v_mov_b32_e32 v56, v143
	v_mov_b32_e32 v57, v143
	v_mov_b32_e32 v58, v143
	v_mov_b32_e32 v59, v143
	v_mov_b32_e32 v60, v143
	v_mov_b32_e32 v61, v143
	v_mov_b32_e32 v62, v143
	v_mov_b32_e32 v63, v143
	v_mov_b32_e32 v64, v143
	v_mov_b32_e32 v65, v143
	v_mov_b32_e32 v66, v143
	v_mov_b32_e32 v67, v143
	v_mov_b32_e32 v68, v143
	v_mov_b32_e32 v69, v143
	v_mov_b32_e32 v70, v143
	v_mov_b32_e32 v71, v143
	v_mov_b32_e32 v72, v143
	v_mov_b32_e32 v73, v143
	v_mov_b32_e32 v74, v143
	v_mov_b32_e32 v75, v143
	v_mov_b32_e32 v76, v143
	v_mov_b32_e32 v77, v143
	v_mov_b32_e32 v78, v143
	v_mov_b32_e32 v79, v143
	v_mov_b32_e32 v80, v143
	v_mov_b32_e32 v81, v143
	v_mov_b32_e32 v82, v143
	v_mov_b32_e32 v83, v143
	v_mov_b32_e32 v84, v143
	v_mov_b32_e32 v85, v143
	v_mov_b32_e32 v86, v143
	v_mov_b32_e32 v87, v143
	v_mov_b32_e32 v88, v143
	v_mov_b32_e32 v89, v143
	v_mov_b32_e32 v90, v143
	v_mov_b32_e32 v91, v143
	v_mov_b32_e32 v92, v143
	v_mov_b32_e32 v93, v143
	v_mov_b32_e32 v94, v143
	v_mov_b32_e32 v95, v143
	v_mov_b32_e32 v96, v143
	v_mov_b32_e32 v97, v143
	v_mov_b32_e32 v98, v143
	v_mov_b32_e32 v99, v143
	v_mov_b32_e32 v100, v143
	v_mov_b32_e32 v101, v143
	v_mov_b32_e32 v102, v143
	v_mov_b32_e32 v103, v143
	v_mov_b32_e32 v104, v143
	v_mov_b32_e32 v105, v143
	v_mov_b32_e32 v106, v143
	v_mov_b32_e32 v107, v143
	v_mov_b32_e32 v108, v143
	v_mov_b32_e32 v109, v143
	v_mov_b32_e32 v110, v143
	v_mov_b32_e32 v111, v143
	v_mov_b32_e32 v112, v143
	v_mov_b32_e32 v113, v143
	v_mov_b32_e32 v114, v143
	v_mov_b32_e32 v115, v143
	v_mov_b32_e32 v116, v143
	v_mov_b32_e32 v117, v143
	v_mov_b32_e32 v118, v143
	v_mov_b32_e32 v119, v143
	v_mov_b32_e32 v120, v143
	v_mov_b32_e32 v121, v143
	v_mov_b32_e32 v122, v143
	v_mov_b32_e32 v123, v143
	v_mov_b32_e32 v124, v143
	v_mov_b32_e32 v125, v143
	v_mov_b32_e32 v126, v143
	v_mov_b32_e32 v127, v143
	v_mov_b32_e32 v128, v143
	v_mov_b32_e32 v129, v143
	v_readfirstlane_b32 s50, v0
	s_nop 3
	s_cmpk_lt_u32 s50, 0x100
	s_cbranch_scc1 .Lprio_skip0
	s_setprio 1
; #define GLDS_STAGE(st, kt_) do { \
;         _Pragma("unroll") for (int i_ = 0; i_ < FI; ++i_) { \
;             glds16(ap + (size_t)(32 * i_) * lda + (kt_) * 64, l3a + (st) + tid * 16 + i_ * 4096); \
;             glds16(bp + (size_t)(32 * i_) * ldb + (kt_) * 64, l3a + (st) + OPB + tid * 16 + i_ * 4096); } } while (0)
; #define GLDS_STAGE(st, kt_) do { \
;         _Pragma("unroll") for (int i_ = 0; i_ < 4; ++i_) { \
;             glds16(ap + (size_t)(64 * i_) * lda + (kt_) * 64, l3a + (st) + tid * 16 + i_ * 8192); \
;             glds16(bp + (size_t)(64 * i_) * ldb + (kt_) * 64, l3a + (st) + 32768 + tid * 16 + i_ * 8192); } } while (0)
; template <class Epi>
; DEV void gemm256_tile(const bf16_t* __restrict__ A, int lda, const bf16_t* __restrict__ Bt, int ldb, int K, unsigned char* lds, const Epi& epi) {
;     ...
;     for (int kt = 0; kt < nk; ++kt) {
;         const int cur = (kt & 1) * 65536;
;         asm volatile("s_waitcnt vmcnt(0)" ::: "memory");
;         __syncthreads();
;         if (kt + 1 < nk) GLDS_STAGE(cur ^ 65536, kt + 1);
; #pragma unroll
;         for (int kh = 0; kh < 2; ++kh) {
;             bf16x8 bfr[4];
;             const int ch = ((kh * 4 + fq) ^ sw) << 4;
; #pragma unroll
;             for (int i = 0; i < 4; ++i) bfr[i] = *(const bf16x8*)(lds + cur + boff + i * 2048 + ch);
; #pragma unroll
;             for (int mh = 0; mh < 2; ++mh) {
;                 bf16x8 af[4];
; #pragma unroll
;                 for (int i = 0; i < 4; ++i) af[i] = *(const bf16x8*)(lds + cur + aoff + (mh * 4 + i) * 2048 + ch);
; #pragma unroll
;                 for (int mi = 0; mi < 4; ++mi)
; #pragma unroll
;                     for (int ni = 0; ni < 4; ++ni) acc[mh * 4 + mi][ni] = __builtin_amdgcn_mfma_f32_16x16x32_bf16(bfr[ni], af[mi], acc[mh * 4 + mi][ni], 0, 0, 0);
;             }
;         }
;     }
.Lprio_skip0:
.LBB0_174:
	s_and_b32 s48, s21, 0x10000
	s_xor_b32 s49, s48, 0x10000
	v_add_u32_e32 v216, s49, v142
	v_add_u32_e32 v217, s49, v156
	s_waitcnt vmcnt(0) lgkmcnt(0)
	s_barrier
	v_or_b32_e32 v248, s48, v175
	v_add_u32_e32 v249, s48, v157
	v_add_u32_e32 v244, v248, v174
	v_add_u32_e32 v245, v249, v174
	ds_read_b128 v[176:179], v244 offset:32768
	ds_read_b128 v[180:183], v244 offset:34816
	ds_read_b128 v[184:187], v244 offset:36864
	ds_read_b128 v[188:191], v244 offset:38912
	ds_read_b128 v[228:231], v245
	ds_read_b128 v[232:235], v245 offset:2048
	ds_read_b128 v[236:239], v245 offset:4096
	ds_read_b128 v[240:243], v245 offset:6144
	v_readfirstlane_b32 s40, v216
	v_readfirstlane_b32 s44, v217
	v_add_u32_e32 v246, v248, v155
	v_add_u32_e32 v247, v249, v155
	s_mov_b32 m0, s40
	v_lshl_add_u64 v[204:205], v[144:145], 0, s[4:5]
	global_load_lds_dwordx4 v[144:145], off
	s_mov_b32 m0, s44
	v_lshl_add_u64 v[210:211], v[146:147], 0, s[4:5]
	global_load_lds_dwordx4 v[146:147], off
	s_add_i32 s41, s40, 0x2000
	s_add_i32 s45, s44, 0x2000
	s_add_i32 s42, s40, 0x4000
	s_add_i32 s46, s44, 0x4000
	s_add_i32 s43, s40, 0x6000
	s_add_i32 s47, s44, 0x6000
	s_add_i32 s21, s21, 0x10000
	s_waitcnt lgkmcnt(3)
	v_mfma_f32_16x16x32_bf16 v[126:129], v[176:179], v[228:231], v[126:129]
	v_lshl_add_u64 v[206:207], v[144:145], 0, s[6:7]
	v_mfma_f32_16x16x32_bf16 v[122:125], v[180:183], v[228:231], v[122:125]
	v_lshl_add_u64 v[212:213], v[146:147], 0, s[6:7]
	v_mfma_f32_16x16x32_bf16 v[118:121], v[184:187], v[228:231], v[118:121]
	v_lshl_add_u64 v[208:209], v[144:145], 0, s[8:9]
	v_mfma_f32_16x16x32_bf16 v[114:117], v[188:191], v[228:231], v[114:117]
	v_lshl_add_u64 v[214:215], v[146:147], 0, s[8:9]
	s_waitcnt lgkmcnt(2)
	v_mfma_f32_16x16x32_bf16 v[110:113], v[176:179], v[232:235], v[110:113]
	v_mfma_f32_16x16x32_bf16 v[106:109], v[180:183], v[232:235], v[106:109]
	v_mfma_f32_16x16x32_bf16 v[102:105], v[184:187], v[232:235], v[102:105]
	v_mfma_f32_16x16x32_bf16 v[98:101], v[188:191], v[232:235], v[98:101]
	s_waitcnt lgkmcnt(1)
	v_mfma_f32_16x16x32_bf16 v[94:97], v[176:179], v[236:239], v[94:97]
	ds_read_b128 v[228:231], v245 offset:8192
	v_mfma_f32_16x16x32_bf16 v[90:93], v[180:183], v[236:239], v[90:93]
	ds_read_b128 v[232:235], v245 offset:10240
	v_mfma_f32_16x16x32_bf16 v[86:89], v[184:187], v[236:239], v[86:89]
	s_mov_b32 m0, s41
	v_mfma_f32_16x16x32_bf16 v[82:85], v[188:191], v[236:239], v[82:85]
	global_load_lds_dwordx4 v[204:205], off
	s_waitcnt lgkmcnt(2)
	v_mfma_f32_16x16x32_bf16 v[78:81], v[176:179], v[240:243], v[78:81]
	s_mov_b32 m0, s45
	v_mfma_f32_16x16x32_bf16 v[74:77], v[180:183], v[240:243], v[74:77]
	global_load_lds_dwordx4 v[210:211], off
	v_mfma_f32_16x16x32_bf16 v[70:73], v[184:187], v[240:243], v[70:73]
	v_mfma_f32_16x16x32_bf16 v[66:69], v[188:191], v[240:243], v[66:69]
	s_waitcnt lgkmcnt(1)
	v_mfma_f32_16x16x32_bf16 v[62:65], v[176:179], v[228:231], v[62:65]
	ds_read_b128 v[236:239], v245 offset:12288
	v_mfma_f32_16x16x32_bf16 v[58:61], v[180:183], v[228:231], v[58:61]
	ds_read_b128 v[240:243], v245 offset:14336
	v_mfma_f32_16x16x32_bf16 v[54:57], v[184:187], v[228:231], v[54:57]
	s_mov_b32 m0, s42
	v_mfma_f32_16x16x32_bf16 v[50:53], v[188:191], v[228:231], v[50:53]
	global_load_lds_dwordx4 v[206:207], off
	s_waitcnt lgkmcnt(2)
	v_mfma_f32_16x16x32_bf16 v[46:49], v[176:179], v[232:235], v[46:49]
	s_mov_b32 m0, s46
	v_mfma_f32_16x16x32_bf16 v[42:45], v[180:183], v[232:235], v[42:45]
	global_load_lds_dwordx4 v[212:213], off
	v_mfma_f32_16x16x32_bf16 v[34:37], v[184:187], v[232:235], v[34:37]
	v_mfma_f32_16x16x32_bf16 v[30:33], v[188:191], v[232:235], v[30:33]
	s_waitcnt lgkmcnt(1)
	v_mfma_f32_16x16x32_bf16 v[26:29], v[176:179], v[236:239], v[26:29]
	ds_read_b128 v[192:195], v246 offset:32768
	v_mfma_f32_16x16x32_bf16 v[22:25], v[180:183], v[236:239], v[22:25]
	ds_read_b128 v[196:199], v246 offset:34816
	v_mfma_f32_16x16x32_bf16 v[18:21], v[184:187], v[236:239], v[18:21]
	ds_read_b128 v[220:223], v246 offset:36864
	v_mfma_f32_16x16x32_bf16 v[14:17], v[188:191], v[236:239], v[14:17]
	ds_read_b128 v[224:227], v246 offset:38912
	s_waitcnt lgkmcnt(4)
	v_mfma_f32_16x16x32_bf16 v[10:13], v[176:179], v[240:243], v[10:13]
	ds_read_b128 v[228:231], v247
	v_mfma_f32_16x16x32_bf16 v[6:9], v[180:183], v[240:243], v[6:9]
	ds_read_b128 v[232:235], v247 offset:2048
	v_mfma_f32_16x16x32_bf16 v[2:5], v[184:187], v[240:243], v[2:5]
	s_mov_b32 m0, s43
	v_mfma_f32_16x16x32_bf16 v[38:41], v[188:191], v[240:243], v[38:41]
	global_load_lds_dwordx4 v[208:209], off
	s_mov_b32 m0, s47
	v_lshl_add_u64 v[144:145], v[144:145], 0, s[10:11]
	global_load_lds_dwordx4 v[214:215], off
	v_lshl_add_u64 v[146:147], v[146:147], 0, s[10:11]
	s_waitcnt lgkmcnt(1)
	v_mfma_f32_16x16x32_bf16 v[126:129], v[192:195], v[228:231], v[126:129]
	ds_read_b128 v[236:239], v247 offset:4096
	v_mfma_f32_16x16x32_bf16 v[122:125], v[196:199], v[228:231], v[122:125]
	ds_read_b128 v[240:243], v247 offset:6144
	v_mfma_f32_16x16x32_bf16 v[118:121], v[220:223], v[228:231], v[118:121]
	v_mfma_f32_16x16x32_bf16 v[114:117], v[224:227], v[228:231], v[114:117]
	s_waitcnt lgkmcnt(2)
	v_mfma_f32_16x16x32_bf16 v[110:113], v[192:195], v[232:235], v[110:113]
	v_mfma_f32_16x16x32_bf16 v[106:109], v[196:199], v[232:235], v[106:109]
	v_mfma_f32_16x16x32_bf16 v[102:105], v[220:223], v[232:235], v[102:105]
	v_mfma_f32_16x16x32_bf16 v[98:101], v[224:227], v[232:235], v[98:101]
	s_waitcnt lgkmcnt(1)
	v_mfma_f32_16x16x32_bf16 v[94:97], v[192:195], v[236:239], v[94:97]
	ds_read_b128 v[228:231], v247 offset:8192
	v_mfma_f32_16x16x32_bf16 v[90:93], v[196:199], v[236:239], v[90:93]
	ds_read_b128 v[232:235], v247 offset:10240
	v_mfma_f32_16x16x32_bf16 v[86:89], v[220:223], v[236:239], v[86:89]
	v_mfma_f32_16x16x32_bf16 v[82:85], v[224:227], v[236:239], v[82:85]
	s_waitcnt lgkmcnt(2)
; DEV unsigned cvt_pk_bf16(float lo, float hi) { const f32x2_t v = {lo, hi}; const bf16x2_t b = __builtin_convertvector(v, bf16x2_t); return __builtin_bit_cast(unsigned, b); }
; #define GLDS_STAGE(st, kt_) do { \
;         _Pragma("unroll") for (int i_ = 0; i_ < FI; ++i_) { \
;             glds16(ap + (size_t)(32 * i_) * lda + (kt_) * 64, l3a + (st) + tid * 16 + i_ * 4096); \
;             glds16(bp + (size_t)(32 * i_) * ldb + (kt_) * 64, l3a + (st) + OPB + tid * 16 + i_ * 4096); } } while (0)
; template <class Epi>
; DEV void gemm256_tile(const bf16_t* __restrict__ A, int lda, const bf16_t* __restrict__ Bt, int ldb, int K, unsigned char* lds, const Epi& epi) {
;     ...
;     for (int kt = 0; kt < nk; ++kt) {
;         const int cur = (kt & 1) * 65536;
;         asm volatile("s_waitcnt vmcnt(0)" ::: "memory");
;         __syncthreads();
;         if (kt + 1 < nk) GLDS_STAGE(cur ^ 65536, kt + 1);
; #pragma unroll
;         for (int kh = 0; kh < 2; ++kh) {
;             bf16x8 bfr[4];
;             const int ch = ((kh * 4 + fq) ^ sw) << 4;
; #pragma unroll
;             for (int i = 0; i < 4; ++i) bfr[i] = *(const bf16x8*)(lds + cur + boff + i * 2048 + ch);
; #pragma unroll
;             for (int mh = 0; mh < 2; ++mh) {
;                 bf16x8 af[4];
; #pragma unroll
;                 for (int i = 0; i < 4; ++i) af[i] = *(const bf16x8*)(lds + cur + aoff + (mh * 4 + i) * 2048 + ch);
; #pragma unroll
;                 for (int mi = 0; mi < 4; ++mi)
; #pragma unroll
;                     for (int ni = 0; ni < 4; ++ni) acc[mh * 4 + mi][ni] = __builtin_amdgcn_mfma_f32_16x16x32_bf16(bfr[ni], af[mi], acc[mh * 4 + mi][ni], 0, 0, 0);
;             }
;         }
;     }
;     ...
;     __syncthreads();
;     if constexpr (Epi::STAGE) {
; #pragma unroll
;         for (int mi = 0; mi < 8; ++mi)
; #pragma unroll
;             for (int ni = 0; ni < 4; ++ni) {
;                 const int row = wr * 128 + mi * 16 + fr, col = wc * 64 + ni * 16 + fq * 4;
;                 const f32x4 v = epi.xform(row, col, acc[mi][ni]);
;                 uint2 w; w.x = cvt_pk_bf16(v[0], v[1]); w.y = cvt_pk_bf16(v[2], v[3]);
;                 *(uint2*)(lds + row * 512 + ((((col >> 3) ^ (row & 31)) << 4) | (((col >> 2) & 1) << 3))) = w;
	v_mfma_f32_16x16x32_bf16 v[78:81], v[192:195], v[240:243], v[78:81]
	v_mfma_f32_16x16x32_bf16 v[74:77], v[196:199], v[240:243], v[74:77]
	v_mfma_f32_16x16x32_bf16 v[70:73], v[220:223], v[240:243], v[70:73]
	v_mfma_f32_16x16x32_bf16 v[66:69], v[224:227], v[240:243], v[66:69]
	s_waitcnt lgkmcnt(1)
	v_mfma_f32_16x16x32_bf16 v[62:65], v[192:195], v[228:231], v[62:65]
	ds_read_b128 v[236:239], v247 offset:12288
	v_mfma_f32_16x16x32_bf16 v[58:61], v[196:199], v[228:231], v[58:61]
	ds_read_b128 v[240:243], v247 offset:14336
	v_mfma_f32_16x16x32_bf16 v[54:57], v[220:223], v[228:231], v[54:57]
	v_mfma_f32_16x16x32_bf16 v[50:53], v[224:227], v[228:231], v[50:53]
	s_waitcnt lgkmcnt(2)
	v_mfma_f32_16x16x32_bf16 v[46:49], v[192:195], v[232:235], v[46:49]
	v_mfma_f32_16x16x32_bf16 v[42:45], v[196:199], v[232:235], v[42:45]
	v_mfma_f32_16x16x32_bf16 v[34:37], v[220:223], v[232:235], v[34:37]
	v_mfma_f32_16x16x32_bf16 v[30:33], v[224:227], v[232:235], v[30:33]
	s_waitcnt lgkmcnt(1)
	v_mfma_f32_16x16x32_bf16 v[26:29], v[192:195], v[236:239], v[26:29]
	v_mfma_f32_16x16x32_bf16 v[22:25], v[196:199], v[236:239], v[22:25]
	v_mfma_f32_16x16x32_bf16 v[18:21], v[220:223], v[236:239], v[18:21]
	v_mfma_f32_16x16x32_bf16 v[14:17], v[224:227], v[236:239], v[14:17]
	s_waitcnt lgkmcnt(0)
	v_mfma_f32_16x16x32_bf16 v[10:13], v[192:195], v[240:243], v[10:13]
	v_mfma_f32_16x16x32_bf16 v[6:9], v[196:199], v[240:243], v[6:9]
	v_mfma_f32_16x16x32_bf16 v[2:5], v[220:223], v[240:243], v[2:5]
	v_mfma_f32_16x16x32_bf16 v[38:41], v[224:227], v[240:243], v[38:41]
	s_cmp_eq_u32 s21, 0x1f0000
	s_cbranch_scc0 .LBB0_174
	s_setprio 0
	v_or_b32_e32 v156, 0x18000, v175
	v_add_u32_e32 v157, 0x10000, v157
	v_add_u32_e32 v186, v156, v174
	v_add_u32_e32 v194, v157, v174
	s_waitcnt vmcnt(0)
	s_barrier
	ds_read_b128 v[144:147], v186
	ds_read_b128 v[178:181], v186 offset:2048
	ds_read_b128 v[174:177], v194
	ds_read_b128 v[182:185], v186 offset:4096
	ds_read_b128 v[186:189], v186 offset:6144
	s_waitcnt lgkmcnt(2)
	v_mfma_f32_16x16x32_bf16 v[126:129], v[144:147], v[174:177], v[126:129]
	s_sext_i32_i16 s20, s20
	s_lshl_b32 s20, s20, 8
	s_ashr_i32 s21, s20, 31
	v_mfma_f32_16x16x32_bf16 v[122:125], v[178:181], v[174:177], v[122:125]
	s_waitcnt lgkmcnt(1)
	v_mfma_f32_16x16x32_bf16 v[118:121], v[182:185], v[174:177], v[118:121]
	s_waitcnt lgkmcnt(0)
	v_mfma_f32_16x16x32_bf16 v[114:117], v[186:189], v[174:177], v[114:117]
	ds_read_b128 v[174:177], v194 offset:2048
	s_waitcnt lgkmcnt(0)
	v_mfma_f32_16x16x32_bf16 v[110:113], v[144:147], v[174:177], v[110:113]
	v_mfma_f32_16x16x32_bf16 v[106:109], v[178:181], v[174:177], v[106:109]
	v_mfma_f32_16x16x32_bf16 v[102:105], v[182:185], v[174:177], v[102:105]
	v_mfma_f32_16x16x32_bf16 v[98:101], v[186:189], v[174:177], v[98:101]
	ds_read_b128 v[174:177], v194 offset:4096
	s_waitcnt lgkmcnt(0)
	v_mfma_f32_16x16x32_bf16 v[94:97], v[144:147], v[174:177], v[94:97]
	v_mfma_f32_16x16x32_bf16 v[90:93], v[178:181], v[174:177], v[90:93]
	v_mfma_f32_16x16x32_bf16 v[86:89], v[182:185], v[174:177], v[86:89]
	v_mfma_f32_16x16x32_bf16 v[82:85], v[186:189], v[174:177], v[82:85]
	ds_read_b128 v[174:177], v194 offset:6144
	s_waitcnt lgkmcnt(0)
	v_mfma_f32_16x16x32_bf16 v[78:81], v[144:147], v[174:177], v[78:81]
	v_mfma_f32_16x16x32_bf16 v[74:77], v[178:181], v[174:177], v[74:77]
	v_mfma_f32_16x16x32_bf16 v[70:73], v[182:185], v[174:177], v[70:73]
	v_mfma_f32_16x16x32_bf16 v[66:69], v[186:189], v[174:177], v[66:69]
	ds_read_b128 v[174:177], v194 offset:8192
	ds_read_b128 v[190:193], v194 offset:10240
	s_waitcnt lgkmcnt(1)
	v_mfma_f32_16x16x32_bf16 v[62:65], v[144:147], v[174:177], v[62:65]
	v_mfma_f32_16x16x32_bf16 v[58:61], v[178:181], v[174:177], v[58:61]
	v_mfma_f32_16x16x32_bf16 v[54:57], v[182:185], v[174:177], v[54:57]
	v_mfma_f32_16x16x32_bf16 v[50:53], v[186:189], v[174:177], v[50:53]
	ds_read_b128 v[174:177], v194 offset:12288
	s_waitcnt lgkmcnt(1)
	v_mfma_f32_16x16x32_bf16 v[46:49], v[144:147], v[190:193], v[46:49]
	v_mfma_f32_16x16x32_bf16 v[42:45], v[178:181], v[190:193], v[42:45]
	v_mfma_f32_16x16x32_bf16 v[34:37], v[182:185], v[190:193], v[34:37]
	v_mfma_f32_16x16x32_bf16 v[30:33], v[186:189], v[190:193], v[30:33]
	ds_read_b128 v[190:193], v194 offset:14336
	s_waitcnt lgkmcnt(1)
	v_mfma_f32_16x16x32_bf16 v[194:197], v[144:147], v[174:177], v[26:29]
	s_nop 2
	v_add_u32_e32 v29, v156, v155
	ds_read_b128 v[198:201], v29
	ds_read_b128 v[202:205], v29 offset:2048
	ds_read_b128 v[206:209], v29 offset:4096
	ds_read_b128 v[210:213], v29 offset:6144
	v_add_u32_e32 v29, v157, v155
	v_mfma_f32_16x16x32_bf16 v[22:25], v[178:181], v[174:177], v[22:25]
	v_and_b32_e32 v28, 0xc0, v150
	v_lshl_or_b32 v153, v153, 2, v28
	v_lshlrev_b32_e32 v28, 3, v152
	v_mfma_f32_16x16x32_bf16 v[18:21], v[182:185], v[174:177], v[18:21]
	v_mad_i64_i32 v[26:27], s[22:23], s19, v149, v[172:173]
	v_lshl_add_u64 v[26:27], s[20:21], 1, v[26:27]
	v_mfma_f32_16x16x32_bf16 v[14:17], v[186:189], v[174:177], v[14:17]
	ds_read_b128 v[174:177], v29
	ds_read_b128 v[214:217], v29 offset:2048
	ds_read_b128 v[218:221], v29 offset:4096
	ds_read_b128 v[222:225], v29 offset:6144
	s_mov_b32 s19, 0
	s_waitcnt lgkmcnt(3)
	v_mfma_f32_16x16x32_bf16 v[126:129], v[198:201], v[174:177], v[126:129]
	v_mfma_f32_16x16x32_bf16 v[122:125], v[202:205], v[174:177], v[122:125]
	s_waitcnt lgkmcnt(1)
	v_mfma_f32_16x16x32_bf16 v[94:97], v[198:201], v[218:221], v[94:97]
	v_mfma_f32_16x16x32_bf16 v[10:13], v[144:147], v[190:193], v[10:13]
	ds_read_b128 v[144:147], v29 offset:8192
	ds_read_b128 v[226:229], v29 offset:10240
	ds_read_b128 v[230:233], v29 offset:12288
	ds_read_b128 v[234:237], v29 offset:14336
	v_lshlrev_b32_e32 v29, 9, v154
	v_and_or_b32 v152, v28, 8, v29
	v_mfma_f32_16x16x32_bf16 v[118:121], v[206:209], v[174:177], v[118:121]
	v_cvt_pk_bf16_f32 v28, v126, v127
	v_lshrrev_b32_e32 v126, 3, v153
	v_xor_b32_e32 v127, v126, v151
	v_mfma_f32_16x16x32_bf16 v[90:93], v[202:205], v[218:221], v[90:93]
	v_cvt_pk_bf16_f32 v29, v128, v129
	v_lshl_or_b32 v127, v127, 4, v152
	v_cvt_pk_bf16_f32 v122, v122, v123
	v_mfma_f32_16x16x32_bf16 v[114:117], v[210:213], v[174:177], v[114:117]
	v_cvt_pk_bf16_f32 v123, v124, v125
	v_bitop3_b32 v124, v126, v151, 2 bitop3:0x36
	v_cvt_pk_bf16_f32 v94, v94, v95
	v_mfma_f32_16x16x32_bf16 v[86:89], v[206:209], v[218:221], v[86:89]
	v_cvt_pk_bf16_f32 v95, v96, v97
	s_waitcnt lgkmcnt(0)
	s_barrier
; DEV unsigned cvt_pk_bf16(float lo, float hi) { const f32x2_t v = {lo, hi}; const bf16x2_t b = __builtin_convertvector(v, bf16x2_t); return __builtin_bit_cast(unsigned, b); }
; template <class Epi>
; DEV void gemm256_tile(const bf16_t* __restrict__ A, int lda, const bf16_t* __restrict__ Bt, int ldb, int K, unsigned char* lds, const Epi& epi) {
;     ...
;     __syncthreads();
;     if constexpr (Epi::STAGE) {
; #pragma unroll
;         for (int mi = 0; mi < 8; ++mi)
; #pragma unroll
;             for (int ni = 0; ni < 4; ++ni) {
;                 const int row = wr * 128 + mi * 16 + fr, col = wc * 64 + ni * 16 + fq * 4;
;                 const f32x4 v = epi.xform(row, col, acc[mi][ni]);
;                 uint2 w; w.x = cvt_pk_bf16(v[0], v[1]); w.y = cvt_pk_bf16(v[2], v[3]);
;                 *(uint2*)(lds + row * 512 + ((((col >> 3) ^ (row & 31)) << 4) | (((col >> 2) & 1) << 3))) = w;
;             }
;         __syncthreads();
	v_mfma_f32_16x16x32_bf16 v[110:113], v[198:201], v[214:217], v[110:113]
	v_lshl_add_u32 v124, v124, 4, v152
	v_cvt_pk_bf16_f32 v118, v118, v119
	v_mfma_f32_16x16x32_bf16 v[82:85], v[210:213], v[218:221], v[82:85]
	v_cvt_pk_bf16_f32 v119, v120, v121
	v_bitop3_b32 v120, v126, v151, 4 bitop3:0x36
	ds_write2st64_b64 v127, v[28:29], v[94:95] offset1:32
	v_mfma_f32_16x16x32_bf16 v[106:109], v[202:205], v[214:217], v[106:109]
	v_cvt_pk_bf16_f32 v28, v90, v91
	v_cvt_pk_bf16_f32 v29, v92, v93
	v_lshl_add_u32 v120, v120, 4, v152
	v_mfma_f32_16x16x32_bf16 v[78:81], v[198:201], v[222:225], v[78:81]
	v_cvt_pk_bf16_f32 v114, v114, v115
	v_cvt_pk_bf16_f32 v115, v116, v117
	v_bitop3_b32 v116, v126, v151, 6 bitop3:0x36
	v_mfma_f32_16x16x32_bf16 v[102:105], v[206:209], v[214:217], v[102:105]
	ds_write2st64_b64 v124, v[122:123], v[28:29] offset1:32
	v_cvt_pk_bf16_f32 v28, v86, v87
	v_cvt_pk_bf16_f32 v29, v88, v89
	v_mfma_f32_16x16x32_bf16 v[74:77], v[202:205], v[222:225], v[74:77]
	v_lshl_add_u32 v116, v116, 4, v152
	v_or_b32_e32 v117, 16, v151
	v_cvt_pk_bf16_f32 v110, v110, v111
	v_mfma_f32_16x16x32_bf16 v[2:5], v[182:185], v[190:193], v[2:5]
	v_cvt_pk_bf16_f32 v111, v112, v113
	v_bitop3_b32 v112, v126, v151, 16 bitop3:0x1e
	ds_write2st64_b64 v120, v[118:119], v[28:29] offset1:32
	v_mfma_f32_16x16x32_bf16 v[98:101], v[210:213], v[214:217], v[98:101]
	v_cvt_pk_bf16_f32 v28, v82, v83
	v_cvt_pk_bf16_f32 v29, v84, v85
	v_lshl_or_b32 v112, v112, 4, v152
	v_mfma_f32_16x16x32_bf16 v[70:73], v[206:209], v[222:225], v[70:73]
	v_cvt_pk_bf16_f32 v106, v106, v107
	v_cvt_pk_bf16_f32 v107, v108, v109
	v_bitop3_b32 v108, v126, v117, 2 bitop3:0x36
	v_mfma_f32_16x16x32_bf16 v[66:69], v[210:213], v[222:225], v[66:69]
	ds_write2st64_b64 v116, v[114:115], v[28:29] offset1:32
	v_cvt_pk_bf16_f32 v28, v78, v79
	v_cvt_pk_bf16_f32 v29, v80, v81
	v_lshl_add_u32 v108, v108, 4, v152
	v_cvt_pk_bf16_f32 v102, v102, v103
	v_cvt_pk_bf16_f32 v103, v104, v105
	v_bitop3_b32 v104, v126, v117, 4 bitop3:0x36
	ds_write2st64_b64 v112, v[110:111], v[28:29] offset0:16 offset1:48
	v_cvt_pk_bf16_f32 v28, v74, v75
	v_cvt_pk_bf16_f32 v29, v76, v77
	v_lshl_add_u32 v104, v104, 4, v152
	v_cvt_pk_bf16_f32 v98, v98, v99
	v_cvt_pk_bf16_f32 v99, v100, v101
	v_bitop3_b32 v100, v126, v117, 6 bitop3:0x36
	ds_write2st64_b64 v108, v[106:107], v[28:29] offset0:16 offset1:48
	v_cvt_pk_bf16_f32 v28, v70, v71
	v_cvt_pk_bf16_f32 v29, v72, v73
	v_mfma_f32_16x16x32_bf16 v[34:37], v[206:209], v[226:229], v[34:37]
	v_lshl_add_u32 v100, v100, 4, v152
	ds_write2st64_b64 v104, v[102:103], v[28:29] offset0:16 offset1:48
	v_cvt_pk_bf16_f32 v28, v66, v67
	v_mfma_f32_16x16x32_bf16 v[2:5], v[206:209], v[234:237], v[2:5]
	v_cvt_pk_bf16_f32 v29, v68, v69
	ds_write2st64_b64 v100, v[98:99], v[28:29] offset0:16 offset1:48
	s_nop 1
	v_cvt_pk_bf16_f32 v34, v34, v35
	v_mfma_f32_16x16x32_bf16 v[38:41], v[186:189], v[190:193], v[38:41]
	v_cvt_pk_bf16_f32 v35, v36, v37
	s_nop 0
	v_cvt_pk_bf16_f32 v2, v2, v3
	v_cvt_pk_bf16_f32 v3, v4, v5
	v_mfma_f32_16x16x32_bf16 v[6:9], v[178:181], v[190:193], v[6:9]
	ds_write2st64_b64 v104, v[34:35], v[2:3] offset0:80 offset1:112
	v_mfma_f32_16x16x32_bf16 v[28:31], v[210:213], v[226:229], v[30:33]
	v_mfma_f32_16x16x32_bf16 v[2:5], v[210:213], v[234:237], v[38:41]
	v_mfma_f32_16x16x32_bf16 v[62:65], v[198:201], v[144:147], v[62:65]
	s_nop 5
	v_cvt_pk_bf16_f32 v32, v28, v29
	v_cvt_pk_bf16_f32 v33, v30, v31
	v_cvt_pk_bf16_f32 v2, v2, v3
	v_mfma_f32_16x16x32_bf16 v[58:61], v[202:205], v[144:147], v[58:61]
	v_cvt_pk_bf16_f32 v3, v4, v5
	v_cvt_pk_bf16_f32 v62, v62, v63
	v_cvt_pk_bf16_f32 v63, v64, v65
	v_mfma_f32_16x16x32_bf16 v[54:57], v[206:209], v[144:147], v[54:57]
	ds_write2st64_b64 v100, v[32:33], v[2:3] offset0:80 offset1:112
	s_nop 2
	v_cvt_pk_bf16_f32 v58, v58, v59
	v_cvt_pk_bf16_f32 v59, v60, v61
	v_mfma_f32_16x16x32_bf16 v[50:53], v[210:213], v[144:147], v[50:53]
	v_and_b32_e32 v2, 0x1f0, v142
	v_cvt_pk_bf16_f32 v54, v54, v55
	v_cvt_pk_bf16_f32 v55, v56, v57
	v_mfma_f32_16x16x32_bf16 v[46:49], v[198:201], v[226:229], v[46:49]
	v_mfma_f32_16x16x32_bf16 v[42:45], v[202:205], v[226:229], v[42:45]
	s_nop 2
	v_cvt_pk_bf16_f32 v50, v50, v51
	v_cvt_pk_bf16_f32 v51, v52, v53
	s_nop 1
	v_cvt_pk_bf16_f32 v46, v46, v47
	v_mfma_f32_16x16x32_bf16 v[28:31], v[198:201], v[230:233], v[194:197]
	v_cvt_pk_bf16_f32 v47, v48, v49
	v_cvt_pk_bf16_f32 v42, v42, v43
	v_cvt_pk_bf16_f32 v43, v44, v45
	v_mfma_f32_16x16x32_bf16 v[22:25], v[202:205], v[230:233], v[22:25]
	v_mfma_f32_16x16x32_bf16 v[18:21], v[206:209], v[230:233], v[18:21]
	s_nop 2
	v_cvt_pk_bf16_f32 v28, v28, v29
	v_cvt_pk_bf16_f32 v29, v30, v31
	s_nop 1
	v_cvt_pk_bf16_f32 v22, v22, v23
	v_mfma_f32_16x16x32_bf16 v[14:17], v[210:213], v[230:233], v[14:17]
	v_cvt_pk_bf16_f32 v23, v24, v25
	v_cvt_pk_bf16_f32 v18, v18, v19
	v_cvt_pk_bf16_f32 v19, v20, v21
	v_mfma_f32_16x16x32_bf16 v[10:13], v[198:201], v[234:237], v[10:13]
	ds_write2st64_b64 v127, v[62:63], v[28:29] offset0:64 offset1:96
	s_nop 2
	v_cvt_pk_bf16_f32 v14, v14, v15
	v_cvt_pk_bf16_f32 v15, v16, v17
	v_mfma_f32_16x16x32_bf16 v[6:9], v[202:205], v[234:237], v[6:9]
	ds_write2st64_b64 v124, v[58:59], v[22:23] offset0:64 offset1:96
	v_cvt_pk_bf16_f32 v10, v10, v11
	v_cvt_pk_bf16_f32 v11, v12, v13
	ds_write2st64_b64 v120, v[54:55], v[18:19] offset0:64 offset1:96
	ds_write2st64_b64 v116, v[50:51], v[14:15] offset0:64 offset1:96
	s_nop 2
	v_cvt_pk_bf16_f32 v6, v6, v7
	v_cvt_pk_bf16_f32 v7, v8, v9
	ds_write2st64_b64 v112, v[46:47], v[10:11] offset0:80 offset1:112
	ds_write2st64_b64 v108, v[42:43], v[6:7] offset0:80 offset1:112
	s_waitcnt lgkmcnt(0)
	s_barrier

; #define LAS __attribute__((address_space(3)))
; #define GLDS_STAGE(st, kt_) do { \
;         _Pragma("unroll") for (int i_ = 0; i_ < FI; ++i_) { \
;             glds16(ap + (size_t)(32 * i_) * lda + (kt_) * 64, l3a + (st) + tid * 16 + i_ * 4096); \
;             glds16(bp + (size_t)(32 * i_) * ldb + (kt_) * 64, l3a + (st) + OPB + tid * 16 + i_ * 4096); } } while (0)
; #define GLDS_STAGE(st, kt_) do { \
;         _Pragma("unroll") for (int i_ = 0; i_ < 4; ++i_) { \
;             glds16(ap + (size_t)(64 * i_) * lda + (kt_) * 64, l3a + (st) + tid * 16 + i_ * 8192); \
;             glds16(bp + (size_t)(64 * i_) * ldb + (kt_) * 64, l3a + (st) + 32768 + tid * 16 + i_ * 8192); } } while (0)
; template <class Epi>
; DEV void gemm256_tile(const bf16_t* __restrict__ A, int lda, const bf16_t* __restrict__ Bt, int ldb, int K, unsigned char* lds, const Epi& epi) {
;     int tid = threadIdx.x; asm volatile("" : "+v"(tid)); const int lane = tid & 63, wid = tid >> 6;
;     const int wr = wid >> 2, wc = wid & 3, fr = lane & 15, fq = lane >> 4;
;     f32x4 acc[8][4];
; #pragma unroll
;     for (int i = 0; i < 8; ++i)
; #pragma unroll
;         for (int j = 0; j < 4; ++j) acc[i][j] = (f32x4){0.f, 0.f, 0.f, 0.f};
;     const int lrow = tid >> 3, lcs = (tid & 7) ^ (lrow & 7);
;     const bf16_t* ap = A + (size_t)lrow * lda + lcs * 8;
;     const bf16_t* bp = Bt + (size_t)lrow * ldb + lcs * 8;
;     const unsigned l3a = (unsigned)(size_t)(LAS unsigned char*)lds;
;     const int nk = K >> 6;
;     ...
;     GLDS_STAGE(0, 0);
;     const int aoff = (wr * 128 + fr) * 128, boff = 32768 + (wc * 64 + fr) * 128, sw = fr & 7;
.LBB0_1002:
	s_lshl_b32 s14, s23, 5
	s_and_b32 s14, s14, 0xe0
	s_ashr_i32 s15, s23, 3
	s_add_i32 s14, s14, s15
	s_ashr_i32 s15, s14, 31
	s_lshr_b32 s15, s15, 26
	s_add_i32 s15, s14, s15
	s_ashr_i32 s16, s15, 6
	s_and_b32 s15, s15, 0xffc0
	s_sub_i32 s14, s14, s15
	s_bfe_i32 s15, s14, 0x80000
	s_bfe_u32 s15, s15, 0x3000c
	s_add_i32 s15, s14, s15
	s_bfe_i32 s17, s15, 0x80000
	s_and_b32 s15, s15, 0xf8
	s_sub_i32 s14, s14, s15
	v_mov_b32_e32 v142, v0
	s_lshl_b32 s16, s16, 3
	s_sext_i32_i16 s25, s17
	s_sext_i32_i8 s14, s14
	s_add_i32 s16, s16, s14
	v_ashrrev_i32_e32 v10, 3, v142
	s_ashr_i32 s14, s25, 3
	v_xor_b32_e32 v8, v10, v142
	v_mad_i64_i32 v[2:3], s[26:27], s16, v1, v[174:175]
	v_mad_i64_i32 v[4:5], s[26:27], s14, v1, v[170:171]
	v_lshlrev_b32_e32 v8, 4, v8
	v_mad_i64_i32 v[2:3], s[26:27], v10, s21, v[2:3]
	v_and_b32_e32 v136, 0x70, v8
	v_mad_i64_i32 v[4:5], s[26:27], v10, s21, v[4:5]
	v_lshl_add_u64 v[2:3], v[2:3], 0, v[136:137]
	v_lshl_add_u64 v[4:5], v[4:5], 0, v[136:137]
	v_lshlrev_b32_e32 v136, 4, v142
	s_lshr_b32 s24, s25, 3
	v_add_u32_e32 v150, 0x8000, v136
	v_readfirstlane_b32 s15, v136
	s_mov_b32 s25, m0
	s_mov_b32 m0, s15
	s_nop 0
	global_load_lds_dwordx4 v[2:3], off
	s_mov_b32 m0, s25
	v_lshl_add_u64 v[8:9], v[2:3], 0, s[6:7]
	v_readfirstlane_b32 s25, v150
	s_mov_b32 s26, m0
	s_mov_b32 m0, s25
	s_nop 0
	global_load_lds_dwordx4 v[4:5], off
	s_mov_b32 m0, s26
	s_add_i32 s25, s15, 0x2000
	s_mov_b32 s26, m0
	s_mov_b32 m0, s25
	s_nop 0
	global_load_lds_dwordx4 v[8:9], off
	s_mov_b32 m0, s26
	v_lshl_add_u64 v[8:9], v[4:5], 0, s[6:7]
	s_add_i32 s25, s15, 0xa000
	s_mov_b32 s26, m0
	s_mov_b32 m0, s25
	s_nop 0
	global_load_lds_dwordx4 v[8:9], off
	s_mov_b32 m0, s26
	v_lshl_add_u64 v[8:9], v[2:3], 0, s[8:9]
	s_add_i32 s25, s15, 0x4000
	s_mov_b32 s26, m0
	s_mov_b32 m0, s25
	s_nop 0
	global_load_lds_dwordx4 v[8:9], off
	s_mov_b32 m0, s26
	v_lshl_add_u64 v[8:9], v[4:5], 0, s[8:9]
	s_add_i32 s25, s15, 0xc000
	s_mov_b32 s26, m0
	s_mov_b32 m0, s25
	s_nop 0
	global_load_lds_dwordx4 v[8:9], off
	s_mov_b32 m0, s26
	v_lshl_add_u64 v[2:3], v[2:3], 0, s[10:11]
	s_add_i32 s25, s15, 0x6000
	s_mov_b32 s26, m0
	s_mov_b32 m0, s25
	s_nop 0
	global_load_lds_dwordx4 v[2:3], off
	s_mov_b32 m0, s26
	v_lshl_add_u64 v[2:3], v[4:5], 0, s[10:11]
	v_and_b32_e32 v143, 15, v142
	s_add_i32 s15, s15, 0xe000
	s_mov_b32 s25, m0
	s_mov_b32 m0, s15
	s_nop 0
	global_load_lds_dwordx4 v[2:3], off
	s_mov_b32 m0, s25
	v_ashrrev_i32_e32 v2, 1, v142
	v_and_or_b32 v146, v2, s22, v143
	v_lshlrev_b32_e32 v2, 7, v142
	v_lshrrev_b32_e32 v144, 4, v142
	v_bfe_u32 v145, v142, 4, 2
	v_and_b32_e32 v151, 0x6780, v2
	v_and_b32_e32 v2, 7, v142
	v_mad_i64_i32 v[6:7], s[26:27], v10, s21, 0
	v_bitop3_b32 v3, v144, v2, 3 bitop3:0x6c
	v_bitop3_b32 v2, v145, v2, 4 bitop3:0x36
	v_bitop3_b32 v4, v10, 7, v142 bitop3:0x48
	v_lshlrev_b32_e32 v149, 4, v3
	v_lshlrev_b32_e32 v147, 4, v2
	v_mad_i64_i32 v[2:3], s[26:27], s16, v1, v[6:7]
	v_lshlrev_b32_e32 v4, 4, v4
	v_or_b32_e32 v2, v2, v4
	v_lshl_add_u64 v[138:139], v[132:133], 0, v[2:3]
	v_mad_i64_i32 v[2:3], s[26:27], s14, v1, v[6:7]
	v_or_b32_e32 v2, v2, v4
	s_ashr_i32 s17, s16, 31
	s_mul_hi_i32 s19, s16, 0x108000
	s_mul_i32 s18, s16, 0x108000
	v_lshlrev_b32_e32 v148, 7, v146
	v_lshl_add_u64 v[140:141], v[134:135], 0, v[2:3]
	s_mov_b32 s25, 0
	v_mov_b32_e32 v38, v137
	v_mov_b32_e32 v39, v137
	v_mov_b32_e32 v40, v137
	v_mov_b32_e32 v41, v137
	v_mov_b32_e32 v2, v137
	v_mov_b32_e32 v3, v137
	v_mov_b32_e32 v4, v137
	v_mov_b32_e32 v5, v137
	v_mov_b32_e32 v6, v137
	v_mov_b32_e32 v7, v137
	v_mov_b32_e32 v8, v137
	v_mov_b32_e32 v9, v137
	v_mov_b32_e32 v10, v137
	v_mov_b32_e32 v11, v137
	v_mov_b32_e32 v12, v137
	v_mov_b32_e32 v13, v137
	v_mov_b32_e32 v14, v137
	v_mov_b32_e32 v15, v137
	v_mov_b32_e32 v16, v137
	v_mov_b32_e32 v17, v137
	v_mov_b32_e32 v18, v137
	v_mov_b32_e32 v19, v137
	v_mov_b32_e32 v20, v137
	v_mov_b32_e32 v21, v137
	v_mov_b32_e32 v22, v137
	v_mov_b32_e32 v23, v137
	v_mov_b32_e32 v24, v137
	v_mov_b32_e32 v25, v137
	v_mov_b32_e32 v26, v137
	v_mov_b32_e32 v27, v137
	v_mov_b32_e32 v28, v137
	v_mov_b32_e32 v29, v137
	v_mov_b32_e32 v30, v137
	v_mov_b32_e32 v31, v137
	v_mov_b32_e32 v32, v137
	v_mov_b32_e32 v33, v137
	v_mov_b32_e32 v34, v137
	v_mov_b32_e32 v35, v137
	v_mov_b32_e32 v36, v137
	v_mov_b32_e32 v37, v137
	v_mov_b32_e32 v42, v137
	v_mov_b32_e32 v43, v137
	v_mov_b32_e32 v44, v137
	v_mov_b32_e32 v45, v137
	v_mov_b32_e32 v46, v137
	v_mov_b32_e32 v47, v137
	v_mov_b32_e32 v48, v137
	v_mov_b32_e32 v49, v137
	v_mov_b32_e32 v50, v137
	v_mov_b32_e32 v51, v137
	v_mov_b32_e32 v52, v137
	v_mov_b32_e32 v53, v137
	v_mov_b32_e32 v54, v137
	v_mov_b32_e32 v55, v137
	v_mov_b32_e32 v56, v137
	v_mov_b32_e32 v57, v137
	v_mov_b32_e32 v58, v137
	v_mov_b32_e32 v59, v137
	v_mov_b32_e32 v60, v137
	v_mov_b32_e32 v61, v137
	v_mov_b32_e32 v62, v137
	v_mov_b32_e32 v63, v137
	v_mov_b32_e32 v64, v137
	v_mov_b32_e32 v65, v137
	v_mov_b32_e32 v66, v137
	v_mov_b32_e32 v67, v137
	v_mov_b32_e32 v68, v137
	v_mov_b32_e32 v69, v137
	v_mov_b32_e32 v70, v137
	v_mov_b32_e32 v71, v137
	v_mov_b32_e32 v72, v137
	v_mov_b32_e32 v73, v137
	v_mov_b32_e32 v74, v137
	v_mov_b32_e32 v75, v137
	v_mov_b32_e32 v76, v137
	v_mov_b32_e32 v77, v137
	v_mov_b32_e32 v78, v137
	v_mov_b32_e32 v79, v137
	v_mov_b32_e32 v80, v137
	v_mov_b32_e32 v81, v137
	v_mov_b32_e32 v82, v137
	v_mov_b32_e32 v83, v137
	v_mov_b32_e32 v84, v137
	v_mov_b32_e32 v85, v137
	v_mov_b32_e32 v86, v137
	v_mov_b32_e32 v87, v137
	v_mov_b32_e32 v88, v137
	v_mov_b32_e32 v89, v137
	v_mov_b32_e32 v90, v137
	v_mov_b32_e32 v91, v137
	v_mov_b32_e32 v92, v137
	v_mov_b32_e32 v93, v137
	v_mov_b32_e32 v94, v137
	v_mov_b32_e32 v95, v137
	v_mov_b32_e32 v96, v137
	v_mov_b32_e32 v97, v137
	v_mov_b32_e32 v98, v137
	v_mov_b32_e32 v99, v137
	v_mov_b32_e32 v100, v137
	v_mov_b32_e32 v101, v137
	v_mov_b32_e32 v102, v137
	v_mov_b32_e32 v103, v137
	v_mov_b32_e32 v104, v137
	v_mov_b32_e32 v105, v137
	v_mov_b32_e32 v106, v137
	v_mov_b32_e32 v107, v137
	v_mov_b32_e32 v108, v137
	v_mov_b32_e32 v109, v137
	v_mov_b32_e32 v110, v137
	v_mov_b32_e32 v111, v137
	v_mov_b32_e32 v112, v137
	v_mov_b32_e32 v113, v137
	v_mov_b32_e32 v114, v137
	v_mov_b32_e32 v115, v137
	v_mov_b32_e32 v116, v137
	v_mov_b32_e32 v117, v137
	v_mov_b32_e32 v118, v137
	v_mov_b32_e32 v119, v137
	v_mov_b32_e32 v120, v137
	v_mov_b32_e32 v121, v137
	v_mov_b32_e32 v122, v137
	v_mov_b32_e32 v123, v137
	v_mov_b32_e32 v124, v137
	v_mov_b32_e32 v125, v137
	v_mov_b32_e32 v126, v137
	v_mov_b32_e32 v127, v137
	v_mov_b32_e32 v128, v137
	v_mov_b32_e32 v129, v137
	v_readfirstlane_b32 s50, v0
	s_nop 3
	s_cmpk_lt_u32 s50, 0x100
	s_cbranch_scc1 .Lprio_skip1
	s_setprio 1
; #define GLDS_STAGE(st, kt_) do { \
;         _Pragma("unroll") for (int i_ = 0; i_ < FI; ++i_) { \
;             glds16(ap + (size_t)(32 * i_) * lda + (kt_) * 64, l3a + (st) + tid * 16 + i_ * 4096); \
;             glds16(bp + (size_t)(32 * i_) * ldb + (kt_) * 64, l3a + (st) + OPB + tid * 16 + i_ * 4096); } } while (0)
; #define GLDS_STAGE(st, kt_) do { \
;         _Pragma("unroll") for (int i_ = 0; i_ < 4; ++i_) { \
;             glds16(ap + (size_t)(64 * i_) * lda + (kt_) * 64, l3a + (st) + tid * 16 + i_ * 8192); \
;             glds16(bp + (size_t)(64 * i_) * ldb + (kt_) * 64, l3a + (st) + 32768 + tid * 16 + i_ * 8192); } } while (0)
; template <class Epi>
; DEV void gemm256_tile(const bf16_t* __restrict__ A, int lda, const bf16_t* __restrict__ Bt, int ldb, int K, unsigned char* lds, const Epi& epi) {
;     ...
;     for (int kt = 0; kt < nk; ++kt) {
;         const int cur = (kt & 1) * 65536;
;         asm volatile("s_waitcnt vmcnt(0)" ::: "memory");
;         __syncthreads();
;         if (kt + 1 < nk) GLDS_STAGE(cur ^ 65536, kt + 1);
; #pragma unroll
;         for (int kh = 0; kh < 2; ++kh) {
;             bf16x8 bfr[4];
;             const int ch = ((kh * 4 + fq) ^ sw) << 4;
; #pragma unroll
;             for (int i = 0; i < 4; ++i) bfr[i] = *(const bf16x8*)(lds + cur + boff + i * 2048 + ch);
; #pragma unroll
;             for (int mh = 0; mh < 2; ++mh) {
;                 bf16x8 af[4];
; #pragma unroll
;                 for (int i = 0; i < 4; ++i) af[i] = *(const bf16x8*)(lds + cur + aoff + (mh * 4 + i) * 2048 + ch);
; #pragma unroll
;                 for (int mi = 0; mi < 4; ++mi)
; #pragma unroll
;                     for (int ni = 0; ni < 4; ++ni) acc[mh * 4 + mi][ni] = __builtin_amdgcn_mfma_f32_16x16x32_bf16(bfr[ni], af[mi], acc[mh * 4 + mi][ni], 0, 0, 0);
;             }
;         }
;     }
.Lprio_skip1:
.LBB0_1003:
	s_and_b32 s48, s25, 0x10000
	s_xor_b32 s49, s48, 0x10000
	v_add_u32_e32 v216, s49, v136
	v_add_u32_e32 v217, s49, v150
	s_waitcnt vmcnt(0) lgkmcnt(0)
	s_barrier
	v_or_b32_e32 v248, s48, v151
	v_add_u32_e32 v249, s48, v148
	v_add_u32_e32 v244, v248, v149
	v_add_u32_e32 v245, v249, v149
	ds_read_b128 v[152:155], v244 offset:32768
	ds_read_b128 v[176:179], v244 offset:34816
	ds_read_b128 v[180:183], v244 offset:36864
	ds_read_b128 v[184:187], v244 offset:38912
	ds_read_b128 v[228:231], v245
	ds_read_b128 v[232:235], v245 offset:2048
	ds_read_b128 v[236:239], v245 offset:4096
	ds_read_b128 v[240:243], v245 offset:6144
	v_readfirstlane_b32 s40, v216
	v_readfirstlane_b32 s44, v217
	v_add_u32_e32 v246, v248, v147
	v_add_u32_e32 v247, v249, v147
	s_mov_b32 m0, s40
	v_lshl_add_u64 v[204:205], v[138:139], 0, s[6:7]
	global_load_lds_dwordx4 v[138:139], off
	s_mov_b32 m0, s44
	v_lshl_add_u64 v[210:211], v[140:141], 0, s[6:7]
	global_load_lds_dwordx4 v[140:141], off
	s_add_i32 s41, s40, 0x2000
	s_add_i32 s45, s44, 0x2000
	s_add_i32 s42, s40, 0x4000
	s_add_i32 s46, s44, 0x4000
	s_add_i32 s43, s40, 0x6000
	s_add_i32 s47, s44, 0x6000
	s_add_i32 s25, s25, 0x10000
	s_waitcnt lgkmcnt(3)
	v_mfma_f32_16x16x32_bf16 v[126:129], v[152:155], v[228:231], v[126:129]
	v_lshl_add_u64 v[206:207], v[138:139], 0, s[8:9]
	v_mfma_f32_16x16x32_bf16 v[122:125], v[176:179], v[228:231], v[122:125]
	v_lshl_add_u64 v[212:213], v[140:141], 0, s[8:9]
	v_mfma_f32_16x16x32_bf16 v[118:121], v[180:183], v[228:231], v[118:121]
	v_lshl_add_u64 v[208:209], v[138:139], 0, s[10:11]
	v_mfma_f32_16x16x32_bf16 v[114:117], v[184:187], v[228:231], v[114:117]
	v_lshl_add_u64 v[214:215], v[140:141], 0, s[10:11]
	s_waitcnt lgkmcnt(2)
	v_mfma_f32_16x16x32_bf16 v[110:113], v[152:155], v[232:235], v[110:113]
	v_mfma_f32_16x16x32_bf16 v[106:109], v[176:179], v[232:235], v[106:109]
	v_mfma_f32_16x16x32_bf16 v[102:105], v[180:183], v[232:235], v[102:105]
	v_mfma_f32_16x16x32_bf16 v[98:101], v[184:187], v[232:235], v[98:101]
	s_waitcnt lgkmcnt(1)
	v_mfma_f32_16x16x32_bf16 v[94:97], v[152:155], v[236:239], v[94:97]
	ds_read_b128 v[228:231], v245 offset:8192
	v_mfma_f32_16x16x32_bf16 v[90:93], v[176:179], v[236:239], v[90:93]
	ds_read_b128 v[232:235], v245 offset:10240
	v_mfma_f32_16x16x32_bf16 v[86:89], v[180:183], v[236:239], v[86:89]
	s_mov_b32 m0, s41
	v_mfma_f32_16x16x32_bf16 v[82:85], v[184:187], v[236:239], v[82:85]
	global_load_lds_dwordx4 v[204:205], off
	s_waitcnt lgkmcnt(2)
	v_mfma_f32_16x16x32_bf16 v[78:81], v[152:155], v[240:243], v[78:81]
	s_mov_b32 m0, s45
	v_mfma_f32_16x16x32_bf16 v[74:77], v[176:179], v[240:243], v[74:77]
	global_load_lds_dwordx4 v[210:211], off
	v_mfma_f32_16x16x32_bf16 v[70:73], v[180:183], v[240:243], v[70:73]
	v_mfma_f32_16x16x32_bf16 v[66:69], v[184:187], v[240:243], v[66:69]
	s_waitcnt lgkmcnt(1)
	v_mfma_f32_16x16x32_bf16 v[62:65], v[152:155], v[228:231], v[62:65]
	ds_read_b128 v[236:239], v245 offset:12288
	v_mfma_f32_16x16x32_bf16 v[58:61], v[176:179], v[228:231], v[58:61]
	ds_read_b128 v[240:243], v245 offset:14336
	v_mfma_f32_16x16x32_bf16 v[54:57], v[180:183], v[228:231], v[54:57]
	s_mov_b32 m0, s42
	v_mfma_f32_16x16x32_bf16 v[50:53], v[184:187], v[228:231], v[50:53]
	global_load_lds_dwordx4 v[206:207], off
	s_waitcnt lgkmcnt(2)
	v_mfma_f32_16x16x32_bf16 v[46:49], v[152:155], v[232:235], v[46:49]
	s_mov_b32 m0, s46
	v_mfma_f32_16x16x32_bf16 v[42:45], v[176:179], v[232:235], v[42:45]
	global_load_lds_dwordx4 v[212:213], off
	v_mfma_f32_16x16x32_bf16 v[34:37], v[180:183], v[232:235], v[34:37]
	v_mfma_f32_16x16x32_bf16 v[30:33], v[184:187], v[232:235], v[30:33]
	s_waitcnt lgkmcnt(1)
	v_mfma_f32_16x16x32_bf16 v[26:29], v[152:155], v[236:239], v[26:29]
	ds_read_b128 v[188:191], v246 offset:32768
	v_mfma_f32_16x16x32_bf16 v[22:25], v[176:179], v[236:239], v[22:25]
	ds_read_b128 v[192:195], v246 offset:34816
	v_mfma_f32_16x16x32_bf16 v[18:21], v[180:183], v[236:239], v[18:21]
	ds_read_b128 v[220:223], v246 offset:36864
	v_mfma_f32_16x16x32_bf16 v[14:17], v[184:187], v[236:239], v[14:17]
	ds_read_b128 v[224:227], v246 offset:38912
	s_waitcnt lgkmcnt(4)
	v_mfma_f32_16x16x32_bf16 v[10:13], v[152:155], v[240:243], v[10:13]
	ds_read_b128 v[228:231], v247
	v_mfma_f32_16x16x32_bf16 v[6:9], v[176:179], v[240:243], v[6:9]
	ds_read_b128 v[232:235], v247 offset:2048
	v_mfma_f32_16x16x32_bf16 v[2:5], v[180:183], v[240:243], v[2:5]
	s_mov_b32 m0, s43
	v_mfma_f32_16x16x32_bf16 v[38:41], v[184:187], v[240:243], v[38:41]
	global_load_lds_dwordx4 v[208:209], off
	s_mov_b32 m0, s47
	v_lshl_add_u64 v[138:139], v[138:139], 0, s[12:13]
	global_load_lds_dwordx4 v[214:215], off
	v_lshl_add_u64 v[140:141], v[140:141], 0, s[12:13]
	s_waitcnt lgkmcnt(1)
	v_mfma_f32_16x16x32_bf16 v[126:129], v[188:191], v[228:231], v[126:129]
	ds_read_b128 v[236:239], v247 offset:4096
	v_mfma_f32_16x16x32_bf16 v[122:125], v[192:195], v[228:231], v[122:125]
	ds_read_b128 v[240:243], v247 offset:6144
	v_mfma_f32_16x16x32_bf16 v[118:121], v[220:223], v[228:231], v[118:121]
	v_mfma_f32_16x16x32_bf16 v[114:117], v[224:227], v[228:231], v[114:117]
	s_waitcnt lgkmcnt(2)
	v_mfma_f32_16x16x32_bf16 v[110:113], v[188:191], v[232:235], v[110:113]
	v_mfma_f32_16x16x32_bf16 v[106:109], v[192:195], v[232:235], v[106:109]
	v_mfma_f32_16x16x32_bf16 v[102:105], v[220:223], v[232:235], v[102:105]
	v_mfma_f32_16x16x32_bf16 v[98:101], v[224:227], v[232:235], v[98:101]
	s_waitcnt lgkmcnt(1)
	v_mfma_f32_16x16x32_bf16 v[94:97], v[188:191], v[236:239], v[94:97]
	ds_read_b128 v[228:231], v247 offset:8192
	v_mfma_f32_16x16x32_bf16 v[90:93], v[192:195], v[236:239], v[90:93]
	ds_read_b128 v[232:235], v247 offset:10240
	v_mfma_f32_16x16x32_bf16 v[86:89], v[220:223], v[236:239], v[86:89]
	v_mfma_f32_16x16x32_bf16 v[82:85], v[224:227], v[236:239], v[82:85]
	s_waitcnt lgkmcnt(2)
; DEV unsigned cvt_pk_bf16(float lo, float hi) { const f32x2_t v = {lo, hi}; const bf16x2_t b = __builtin_convertvector(v, bf16x2_t); return __builtin_bit_cast(unsigned, b); }
; #define GLDS_STAGE(st, kt_) do { \
;         _Pragma("unroll") for (int i_ = 0; i_ < FI; ++i_) { \
;             glds16(ap + (size_t)(32 * i_) * lda + (kt_) * 64, l3a + (st) + tid * 16 + i_ * 4096); \
;             glds16(bp + (size_t)(32 * i_) * ldb + (kt_) * 64, l3a + (st) + OPB + tid * 16 + i_ * 4096); } } while (0)
; template <class Epi>
; DEV void gemm256_tile(const bf16_t* __restrict__ A, int lda, const bf16_t* __restrict__ Bt, int ldb, int K, unsigned char* lds, const Epi& epi) {
;     ...
;     for (int kt = 0; kt < nk; ++kt) {
;         const int cur = (kt & 1) * 65536;
;         asm volatile("s_waitcnt vmcnt(0)" ::: "memory");
;         __syncthreads();
;         if (kt + 1 < nk) GLDS_STAGE(cur ^ 65536, kt + 1);
; #pragma unroll
;         for (int kh = 0; kh < 2; ++kh) {
;             bf16x8 bfr[4];
;             const int ch = ((kh * 4 + fq) ^ sw) << 4;
; #pragma unroll
;             for (int i = 0; i < 4; ++i) bfr[i] = *(const bf16x8*)(lds + cur + boff + i * 2048 + ch);
; #pragma unroll
;             for (int mh = 0; mh < 2; ++mh) {
;                 bf16x8 af[4];
; #pragma unroll
;                 for (int i = 0; i < 4; ++i) af[i] = *(const bf16x8*)(lds + cur + aoff + (mh * 4 + i) * 2048 + ch);
; #pragma unroll
;                 for (int mi = 0; mi < 4; ++mi)
; #pragma unroll
;                     for (int ni = 0; ni < 4; ++ni) acc[mh * 4 + mi][ni] = __builtin_amdgcn_mfma_f32_16x16x32_bf16(bfr[ni], af[mi], acc[mh * 4 + mi][ni], 0, 0, 0);
;             }
;         }
;     }
;     ...
;     __syncthreads();
;     if constexpr (Epi::STAGE) {
; #pragma unroll
;         for (int mi = 0; mi < 8; ++mi)
; #pragma unroll
;             for (int ni = 0; ni < 4; ++ni) {
;                 const int row = wr * 128 + mi * 16 + fr, col = wc * 64 + ni * 16 + fq * 4;
;                 const f32x4 v = epi.xform(row, col, acc[mi][ni]);
;                 uint2 w; w.x = cvt_pk_bf16(v[0], v[1]); w.y = cvt_pk_bf16(v[2], v[3]);
;                 *(uint2*)(lds + row * 512 + ((((col >> 3) ^ (row & 31)) << 4) | (((col >> 2) & 1) << 3))) = w;
	v_mfma_f32_16x16x32_bf16 v[78:81], v[188:191], v[240:243], v[78:81]
	v_mfma_f32_16x16x32_bf16 v[74:77], v[192:195], v[240:243], v[74:77]
	v_mfma_f32_16x16x32_bf16 v[70:73], v[220:223], v[240:243], v[70:73]
	v_mfma_f32_16x16x32_bf16 v[66:69], v[224:227], v[240:243], v[66:69]
	s_waitcnt lgkmcnt(1)
	v_mfma_f32_16x16x32_bf16 v[62:65], v[188:191], v[228:231], v[62:65]
	ds_read_b128 v[236:239], v247 offset:12288
	v_mfma_f32_16x16x32_bf16 v[58:61], v[192:195], v[228:231], v[58:61]
	ds_read_b128 v[240:243], v247 offset:14336
	v_mfma_f32_16x16x32_bf16 v[54:57], v[220:223], v[228:231], v[54:57]
	v_mfma_f32_16x16x32_bf16 v[50:53], v[224:227], v[228:231], v[50:53]
	s_waitcnt lgkmcnt(2)
	v_mfma_f32_16x16x32_bf16 v[46:49], v[188:191], v[232:235], v[46:49]
	v_mfma_f32_16x16x32_bf16 v[42:45], v[192:195], v[232:235], v[42:45]
	v_mfma_f32_16x16x32_bf16 v[34:37], v[220:223], v[232:235], v[34:37]
	v_mfma_f32_16x16x32_bf16 v[30:33], v[224:227], v[232:235], v[30:33]
	s_waitcnt lgkmcnt(1)
	v_mfma_f32_16x16x32_bf16 v[26:29], v[188:191], v[236:239], v[26:29]
	v_mfma_f32_16x16x32_bf16 v[22:25], v[192:195], v[236:239], v[22:25]
	v_mfma_f32_16x16x32_bf16 v[18:21], v[220:223], v[236:239], v[18:21]
	v_mfma_f32_16x16x32_bf16 v[14:17], v[224:227], v[236:239], v[14:17]
	s_waitcnt lgkmcnt(0)
	v_mfma_f32_16x16x32_bf16 v[10:13], v[188:191], v[240:243], v[10:13]
	v_mfma_f32_16x16x32_bf16 v[6:9], v[192:195], v[240:243], v[6:9]
	v_mfma_f32_16x16x32_bf16 v[2:5], v[220:223], v[240:243], v[2:5]
	v_mfma_f32_16x16x32_bf16 v[38:41], v[224:227], v[240:243], v[38:41]
	s_cmp_eq_u32 s25, 0x1f0000
	s_cbranch_scc0 .LBB0_1003
	s_setprio 0
	v_or_b32_e32 v172, 0x18000, v151
	v_add_u32_e32 v156, v172, v149
	s_waitcnt vmcnt(0)
	s_barrier
	ds_read_b128 v[138:141], v156
	ds_read_b128 v[152:155], v156 offset:2048
	ds_read_b128 v[176:179], v156 offset:4096
	ds_read_b128 v[180:183], v156 offset:6144
	v_add_u32_e32 v173, 0x10000, v148
	v_add_u32_e32 v188, v173, v149
	ds_read_b128 v[148:151], v188
	s_waitcnt lgkmcnt(0)
	v_mfma_f32_16x16x32_bf16 v[126:129], v[138:141], v[148:151], v[126:129]
	s_sext_i32_i8 s14, s24
	s_lshl_b32 s24, s14, 8
	s_lshl_b64 s[16:17], s[16:17], 21
	v_mfma_f32_16x16x32_bf16 v[122:125], v[152:155], v[148:151], v[122:125]
	s_ashr_i32 s25, s24, 31
	s_add_u32 s14, s4, s16
	s_addc_u32 s15, s5, s17
	v_mfma_f32_16x16x32_bf16 v[118:121], v[176:179], v[148:151], v[118:121]
	s_lshl_b64 s[16:17], s[24:25], 2
	v_lshl_add_u64 v[156:157], v[130:131], 0, s[18:19]
	s_add_u32 s16, s14, s16
	v_mfma_f32_16x16x32_bf16 v[114:117], v[180:183], v[148:151], v[114:117]
	ds_read_b128 v[148:151], v188 offset:2048
	s_addc_u32 s17, s15, s17
	s_mov_b32 s18, 0
	s_waitcnt lgkmcnt(0)
	v_mfma_f32_16x16x32_bf16 v[110:113], v[138:141], v[148:151], v[110:113]
	v_mfma_f32_16x16x32_bf16 v[106:109], v[152:155], v[148:151], v[106:109]
	v_mfma_f32_16x16x32_bf16 v[102:105], v[176:179], v[148:151], v[102:105]
	v_mfma_f32_16x16x32_bf16 v[98:101], v[180:183], v[148:151], v[98:101]
	ds_read_b128 v[148:151], v188 offset:4096
	s_waitcnt lgkmcnt(0)
	v_mfma_f32_16x16x32_bf16 v[94:97], v[138:141], v[148:151], v[94:97]
	v_mfma_f32_16x16x32_bf16 v[90:93], v[152:155], v[148:151], v[90:93]
	v_mfma_f32_16x16x32_bf16 v[86:89], v[176:179], v[148:151], v[86:89]
	v_mfma_f32_16x16x32_bf16 v[82:85], v[180:183], v[148:151], v[82:85]
	ds_read_b128 v[148:151], v188 offset:6144
	s_waitcnt lgkmcnt(0)
	v_mfma_f32_16x16x32_bf16 v[78:81], v[138:141], v[148:151], v[78:81]
	v_mfma_f32_16x16x32_bf16 v[74:77], v[152:155], v[148:151], v[74:77]
	v_mfma_f32_16x16x32_bf16 v[70:73], v[176:179], v[148:151], v[70:73]
	v_mfma_f32_16x16x32_bf16 v[66:69], v[180:183], v[148:151], v[66:69]
	ds_read_b128 v[148:151], v188 offset:8192
	ds_read_b128 v[184:187], v188 offset:10240
	s_waitcnt lgkmcnt(1)
	v_mfma_f32_16x16x32_bf16 v[62:65], v[138:141], v[148:151], v[62:65]
	v_mfma_f32_16x16x32_bf16 v[58:61], v[152:155], v[148:151], v[58:61]
	v_mfma_f32_16x16x32_bf16 v[54:57], v[176:179], v[148:151], v[54:57]
	v_mfma_f32_16x16x32_bf16 v[50:53], v[180:183], v[148:151], v[50:53]
	ds_read_b128 v[148:151], v188 offset:12288
	s_waitcnt lgkmcnt(1)
	v_mfma_f32_16x16x32_bf16 v[46:49], v[138:141], v[184:187], v[46:49]
	v_mfma_f32_16x16x32_bf16 v[42:45], v[152:155], v[184:187], v[42:45]
	v_mfma_f32_16x16x32_bf16 v[34:37], v[176:179], v[184:187], v[34:37]
	v_mfma_f32_16x16x32_bf16 v[30:33], v[180:183], v[184:187], v[30:33]
	ds_read_b128 v[184:187], v188 offset:14336
	s_waitcnt lgkmcnt(1)
	v_mfma_f32_16x16x32_bf16 v[188:191], v[138:141], v[148:151], v[26:29]
	s_nop 2
	v_add_u32_e32 v29, v172, v147
	ds_read_b128 v[192:195], v29
	ds_read_b128 v[196:199], v29 offset:2048
	ds_read_b128 v[200:203], v29 offset:4096
	ds_read_b128 v[204:207], v29 offset:6144
	v_add_u32_e32 v29, v173, v147
	v_mfma_f32_16x16x32_bf16 v[22:25], v[152:155], v[148:151], v[22:25]
	v_and_b32_e32 v28, 0xc0, v142
	v_lshl_or_b32 v145, v145, 2, v28
	v_lshlrev_b32_e32 v28, 3, v144
	v_mfma_f32_16x16x32_bf16 v[18:21], v[176:179], v[148:151], v[18:21]
	v_lshl_add_u64 v[26:27], s[24:25], 1, v[156:157]
	v_mfma_f32_16x16x32_bf16 v[14:17], v[180:183], v[148:151], v[14:17]
	ds_read_b128 v[148:151], v29
	ds_read_b128 v[208:211], v29 offset:2048
	ds_read_b128 v[212:215], v29 offset:4096
	ds_read_b128 v[216:219], v29 offset:6144
	s_waitcnt lgkmcnt(3)
	v_mfma_f32_16x16x32_bf16 v[126:129], v[192:195], v[148:151], v[126:129]
	v_mfma_f32_16x16x32_bf16 v[122:125], v[196:199], v[148:151], v[122:125]
	s_waitcnt lgkmcnt(1)
	v_mfma_f32_16x16x32_bf16 v[94:97], v[192:195], v[212:215], v[94:97]
	v_mfma_f32_16x16x32_bf16 v[10:13], v[138:141], v[184:187], v[10:13]
	ds_read_b128 v[138:141], v29 offset:8192
	ds_read_b128 v[220:223], v29 offset:10240
	ds_read_b128 v[224:227], v29 offset:12288
	ds_read_b128 v[228:231], v29 offset:14336
	v_lshlrev_b32_e32 v29, 9, v146
	v_and_or_b32 v144, v28, 8, v29
	v_mfma_f32_16x16x32_bf16 v[118:121], v[200:203], v[148:151], v[118:121]
	v_cvt_pk_bf16_f32 v28, v126, v127
	v_lshrrev_b32_e32 v126, 3, v145
	v_xor_b32_e32 v127, v126, v143
	v_mfma_f32_16x16x32_bf16 v[90:93], v[196:199], v[212:215], v[90:93]
	v_cvt_pk_bf16_f32 v29, v128, v129
	v_lshl_or_b32 v127, v127, 4, v144
	v_cvt_pk_bf16_f32 v122, v122, v123
	v_mfma_f32_16x16x32_bf16 v[114:117], v[204:207], v[148:151], v[114:117]
	v_cvt_pk_bf16_f32 v123, v124, v125
	v_bitop3_b32 v124, v126, v143, 2 bitop3:0x36
	v_cvt_pk_bf16_f32 v94, v94, v95
	v_mfma_f32_16x16x32_bf16 v[86:89], v[200:203], v[212:215], v[86:89]
	v_cvt_pk_bf16_f32 v95, v96, v97
	s_waitcnt lgkmcnt(0)
	s_barrier
; DEV unsigned cvt_pk_bf16(float lo, float hi) { const f32x2_t v = {lo, hi}; const bf16x2_t b = __builtin_convertvector(v, bf16x2_t); return __builtin_bit_cast(unsigned, b); }
; template <class Epi>
; DEV void gemm256_tile(const bf16_t* __restrict__ A, int lda, const bf16_t* __restrict__ Bt, int ldb, int K, unsigned char* lds, const Epi& epi) {
;     ...
;     __syncthreads();
;     if constexpr (Epi::STAGE) {
; #pragma unroll
;         for (int mi = 0; mi < 8; ++mi)
; #pragma unroll
;             for (int ni = 0; ni < 4; ++ni) {
;                 const int row = wr * 128 + mi * 16 + fr, col = wc * 64 + ni * 16 + fq * 4;
;                 const f32x4 v = epi.xform(row, col, acc[mi][ni]);
;                 uint2 w; w.x = cvt_pk_bf16(v[0], v[1]); w.y = cvt_pk_bf16(v[2], v[3]);
;                 *(uint2*)(lds + row * 512 + ((((col >> 3) ^ (row & 31)) << 4) | (((col >> 2) & 1) << 3))) = w;
;             }
;         __syncthreads();
	v_mfma_f32_16x16x32_bf16 v[110:113], v[192:195], v[208:211], v[110:113]
	v_lshl_add_u32 v124, v124, 4, v144
	v_cvt_pk_bf16_f32 v118, v118, v119
	v_mfma_f32_16x16x32_bf16 v[82:85], v[204:207], v[212:215], v[82:85]
	v_cvt_pk_bf16_f32 v119, v120, v121
	v_bitop3_b32 v120, v126, v143, 4 bitop3:0x36
	ds_write2st64_b64 v127, v[28:29], v[94:95] offset1:32
	v_mfma_f32_16x16x32_bf16 v[106:109], v[196:199], v[208:211], v[106:109]
	v_cvt_pk_bf16_f32 v28, v90, v91
	v_cvt_pk_bf16_f32 v29, v92, v93
	v_lshl_add_u32 v120, v120, 4, v144
	v_mfma_f32_16x16x32_bf16 v[78:81], v[192:195], v[216:219], v[78:81]
	v_cvt_pk_bf16_f32 v114, v114, v115
	v_cvt_pk_bf16_f32 v115, v116, v117
	v_bitop3_b32 v116, v126, v143, 6 bitop3:0x36
	v_mfma_f32_16x16x32_bf16 v[102:105], v[200:203], v[208:211], v[102:105]
	ds_write2st64_b64 v124, v[122:123], v[28:29] offset1:32
	v_cvt_pk_bf16_f32 v28, v86, v87
	v_cvt_pk_bf16_f32 v29, v88, v89
	v_mfma_f32_16x16x32_bf16 v[74:77], v[196:199], v[216:219], v[74:77]
	v_lshl_add_u32 v116, v116, 4, v144
	v_or_b32_e32 v117, 16, v143
	v_cvt_pk_bf16_f32 v110, v110, v111
	v_mfma_f32_16x16x32_bf16 v[2:5], v[176:179], v[184:187], v[2:5]
	v_cvt_pk_bf16_f32 v111, v112, v113
	v_bitop3_b32 v112, v126, v143, 16 bitop3:0x1e
	ds_write2st64_b64 v120, v[118:119], v[28:29] offset1:32
	v_mfma_f32_16x16x32_bf16 v[98:101], v[204:207], v[208:211], v[98:101]
	v_cvt_pk_bf16_f32 v28, v82, v83
	v_cvt_pk_bf16_f32 v29, v84, v85
	v_lshl_or_b32 v112, v112, 4, v144
	v_mfma_f32_16x16x32_bf16 v[70:73], v[200:203], v[216:219], v[70:73]
	v_cvt_pk_bf16_f32 v106, v106, v107
	v_cvt_pk_bf16_f32 v107, v108, v109
	v_bitop3_b32 v108, v126, v117, 2 bitop3:0x36
	v_mfma_f32_16x16x32_bf16 v[66:69], v[204:207], v[216:219], v[66:69]
	ds_write2st64_b64 v116, v[114:115], v[28:29] offset1:32
	v_cvt_pk_bf16_f32 v28, v78, v79
	v_cvt_pk_bf16_f32 v29, v80, v81
	v_lshl_add_u32 v108, v108, 4, v144
	v_cvt_pk_bf16_f32 v102, v102, v103
	v_cvt_pk_bf16_f32 v103, v104, v105
	v_bitop3_b32 v104, v126, v117, 4 bitop3:0x36
	ds_write2st64_b64 v112, v[110:111], v[28:29] offset0:16 offset1:48
	v_cvt_pk_bf16_f32 v28, v74, v75
	v_cvt_pk_bf16_f32 v29, v76, v77
	v_lshl_add_u32 v104, v104, 4, v144
	v_cvt_pk_bf16_f32 v98, v98, v99
	v_cvt_pk_bf16_f32 v99, v100, v101
	v_bitop3_b32 v100, v126, v117, 6 bitop3:0x36
	ds_write2st64_b64 v108, v[106:107], v[28:29] offset0:16 offset1:48
	v_cvt_pk_bf16_f32 v28, v70, v71
	v_cvt_pk_bf16_f32 v29, v72, v73
	v_mfma_f32_16x16x32_bf16 v[34:37], v[200:203], v[220:223], v[34:37]
	v_lshl_add_u32 v100, v100, 4, v144
	ds_write2st64_b64 v104, v[102:103], v[28:29] offset0:16 offset1:48
	v_cvt_pk_bf16_f32 v28, v66, v67
	v_mfma_f32_16x16x32_bf16 v[2:5], v[200:203], v[228:231], v[2:5]
	v_cvt_pk_bf16_f32 v29, v68, v69
	ds_write2st64_b64 v100, v[98:99], v[28:29] offset0:16 offset1:48
	s_nop 1
	v_cvt_pk_bf16_f32 v34, v34, v35
	v_mfma_f32_16x16x32_bf16 v[38:41], v[180:183], v[184:187], v[38:41]
	v_cvt_pk_bf16_f32 v35, v36, v37
	s_nop 0
	v_cvt_pk_bf16_f32 v2, v2, v3
	v_cvt_pk_bf16_f32 v3, v4, v5
	v_mfma_f32_16x16x32_bf16 v[6:9], v[152:155], v[184:187], v[6:9]
	ds_write2st64_b64 v104, v[34:35], v[2:3] offset0:80 offset1:112
	v_mfma_f32_16x16x32_bf16 v[28:31], v[204:207], v[220:223], v[30:33]
	v_mfma_f32_16x16x32_bf16 v[2:5], v[204:207], v[228:231], v[38:41]
	v_mfma_f32_16x16x32_bf16 v[62:65], v[192:195], v[138:141], v[62:65]
	s_nop 5
	v_cvt_pk_bf16_f32 v32, v28, v29
	v_cvt_pk_bf16_f32 v33, v30, v31
	v_cvt_pk_bf16_f32 v2, v2, v3
	v_mfma_f32_16x16x32_bf16 v[58:61], v[196:199], v[138:141], v[58:61]
	v_cvt_pk_bf16_f32 v3, v4, v5
	v_cvt_pk_bf16_f32 v62, v62, v63
	v_cvt_pk_bf16_f32 v63, v64, v65
	v_mfma_f32_16x16x32_bf16 v[54:57], v[200:203], v[138:141], v[54:57]
	ds_write2st64_b64 v100, v[32:33], v[2:3] offset0:80 offset1:112
	s_nop 2
	v_cvt_pk_bf16_f32 v58, v58, v59
	v_cvt_pk_bf16_f32 v59, v60, v61
	v_mfma_f32_16x16x32_bf16 v[50:53], v[204:207], v[138:141], v[50:53]
	v_and_b32_e32 v2, 0x1f0, v136
	v_cvt_pk_bf16_f32 v54, v54, v55
	v_cvt_pk_bf16_f32 v55, v56, v57
	v_mfma_f32_16x16x32_bf16 v[46:49], v[192:195], v[220:223], v[46:49]
	v_mfma_f32_16x16x32_bf16 v[42:45], v[196:199], v[220:223], v[42:45]
	s_nop 2
	v_cvt_pk_bf16_f32 v50, v50, v51
	v_cvt_pk_bf16_f32 v51, v52, v53
	s_nop 1
	v_cvt_pk_bf16_f32 v46, v46, v47
	v_mfma_f32_16x16x32_bf16 v[28:31], v[192:195], v[224:227], v[188:191]
	v_cvt_pk_bf16_f32 v47, v48, v49
	v_cvt_pk_bf16_f32 v42, v42, v43
	v_cvt_pk_bf16_f32 v43, v44, v45
	v_mfma_f32_16x16x32_bf16 v[22:25], v[196:199], v[224:227], v[22:25]
	v_mfma_f32_16x16x32_bf16 v[18:21], v[200:203], v[224:227], v[18:21]
	s_nop 2
	v_cvt_pk_bf16_f32 v28, v28, v29
	v_cvt_pk_bf16_f32 v29, v30, v31
	s_nop 1
	v_cvt_pk_bf16_f32 v22, v22, v23
	v_mfma_f32_16x16x32_bf16 v[14:17], v[204:207], v[224:227], v[14:17]
	v_cvt_pk_bf16_f32 v23, v24, v25
	v_cvt_pk_bf16_f32 v18, v18, v19
	v_cvt_pk_bf16_f32 v19, v20, v21
	v_mfma_f32_16x16x32_bf16 v[10:13], v[192:195], v[228:231], v[10:13]
	ds_write2st64_b64 v127, v[62:63], v[28:29] offset0:64 offset1:96
	s_nop 2
	v_cvt_pk_bf16_f32 v14, v14, v15
	v_cvt_pk_bf16_f32 v15, v16, v17
	v_mfma_f32_16x16x32_bf16 v[6:9], v[196:199], v[228:231], v[6:9]
	ds_write2st64_b64 v124, v[58:59], v[22:23] offset0:64 offset1:96
	v_cvt_pk_bf16_f32 v10, v10, v11
	v_cvt_pk_bf16_f32 v11, v12, v13
	ds_write2st64_b64 v120, v[54:55], v[18:19] offset0:64 offset1:96
	ds_write2st64_b64 v116, v[50:51], v[14:15] offset0:64 offset1:96
	s_nop 2
	v_cvt_pk_bf16_f32 v6, v6, v7
	v_cvt_pk_bf16_f32 v7, v8, v9
	ds_write2st64_b64 v112, v[46:47], v[10:11] offset0:80 offset1:112
	ds_write2st64_b64 v108, v[42:43], v[6:7] offset0:80 offset1:112
	s_waitcnt lgkmcnt(0)
	s_barrier

; #define LAS __attribute__((address_space(3)))
; #define GLDS_STAGE(st, kt_) do { \
;         _Pragma("unroll") for (int i_ = 0; i_ < FI; ++i_) { \
;             glds16(ap + (size_t)(32 * i_) * lda + (kt_) * 64, l3a + (st) + tid * 16 + i_ * 4096); \
;             glds16(bp + (size_t)(32 * i_) * ldb + (kt_) * 64, l3a + (st) + OPB + tid * 16 + i_ * 4096); } } while (0)
; #define GLDS_STAGE(st, kt_) do { \
;         _Pragma("unroll") for (int i_ = 0; i_ < 4; ++i_) { \
;             glds16(ap + (size_t)(64 * i_) * lda + (kt_) * 64, l3a + (st) + tid * 16 + i_ * 8192); \
;             glds16(bp + (size_t)(64 * i_) * ldb + (kt_) * 64, l3a + (st) + 32768 + tid * 16 + i_ * 8192); } } while (0)
; template <class Epi>
; DEV void gemm256_tile(const bf16_t* __restrict__ A, int lda, const bf16_t* __restrict__ Bt, int ldb, int K, unsigned char* lds, const Epi& epi) {
;     int tid = threadIdx.x; asm volatile("" : "+v"(tid)); const int lane = tid & 63, wid = tid >> 6;
;     const int wr = wid >> 2, wc = wid & 3, fr = lane & 15, fq = lane >> 4;
;     f32x4 acc[8][4];
; #pragma unroll
;     for (int i = 0; i < 8; ++i)
; #pragma unroll
;         for (int j = 0; j < 4; ++j) acc[i][j] = (f32x4){0.f, 0.f, 0.f, 0.f};
;     const int lrow = tid >> 3, lcs = (tid & 7) ^ (lrow & 7);
;     const bf16_t* ap = A + (size_t)lrow * lda + lcs * 8;
;     const bf16_t* bp = Bt + (size_t)lrow * ldb + lcs * 8;
;     const unsigned l3a = (unsigned)(size_t)(LAS unsigned char*)lds;
;     const int nk = K >> 6;
;     ...
;     GLDS_STAGE(0, 0);
;     const int aoff = (wr * 128 + fr) * 128, boff = 32768 + (wc * 64 + fr) * 128, sw = fr & 7;
.LBB0_1235:
	s_lshl_b32 s12, s19, 5
	s_and_b32 s12, s12, 0xe0
	s_ashr_i32 s13, s19, 3
	s_add_i32 s12, s12, s13
	s_ashr_i32 s13, s12, 31
	s_lshr_b32 s13, s13, 26
	s_add_i32 s13, s12, s13
	s_ashr_i32 s14, s13, 6
	s_and_b32 s13, s13, 0xffc0
	s_sub_i32 s12, s12, s13
	s_bfe_i32 s13, s12, 0x80000
	s_bfe_u32 s13, s13, 0x3000c
	s_add_i32 s13, s12, s13
	s_bfe_i32 s15, s13, 0x80000
	s_and_b32 s13, s13, 0xf8
	s_sub_i32 s12, s12, s13
	v_mov_b32_e32 v144, v0
	s_lshl_b32 s14, s14, 3
	s_sext_i32_i16 s15, s15
	s_sext_i32_i8 s12, s12
	s_lshr_b32 s20, s15, 3
	v_ashrrev_i32_e32 v10, 3, v144
	s_add_i32 s14, s14, s12
	s_ashr_i32 s15, s15, 3
	v_xor_b32_e32 v8, v10, v144
	v_mad_i64_i32 v[2:3], s[22:23], s14, v1, v[166:167]
	v_mad_i64_i32 v[4:5], s[22:23], s15, v1, v[164:165]
	v_lshlrev_b32_e32 v8, 4, v8
	v_mad_i64_i32 v[2:3], s[22:23], v10, s16, v[2:3]
	v_and_b32_e32 v138, 0x70, v8
	v_mad_i64_i32 v[4:5], s[22:23], v10, s16, v[4:5]
	v_lshl_add_u64 v[2:3], v[2:3], 0, v[138:139]
	v_lshl_add_u64 v[4:5], v[4:5], 0, v[138:139]
	v_lshlrev_b32_e32 v138, 4, v144
	v_mad_i64_i32 v[6:7], s[22:23], v10, s16, 0
	v_add_u32_e32 v150, 0x8000, v138
	v_readfirstlane_b32 s21, v138
	s_mov_b32 s22, m0
	s_mov_b32 m0, s21
	s_nop 0
	global_load_lds_dwordx4 v[2:3], off
	s_mov_b32 m0, s22
	v_lshl_add_u64 v[8:9], v[2:3], 0, s[4:5]
	v_readfirstlane_b32 s22, v150
	s_mov_b32 s23, m0
	s_mov_b32 m0, s22
	s_nop 0
	global_load_lds_dwordx4 v[4:5], off
	s_mov_b32 m0, s23
	s_add_i32 s22, s21, 0x2000
	s_mov_b32 s23, m0
	s_mov_b32 m0, s22
	s_nop 0
	global_load_lds_dwordx4 v[8:9], off
	s_mov_b32 m0, s23
	v_lshl_add_u64 v[8:9], v[4:5], 0, s[4:5]
	s_add_i32 s22, s21, 0xa000
	s_mov_b32 s23, m0
	s_mov_b32 m0, s22
	s_nop 0
	global_load_lds_dwordx4 v[8:9], off
	s_mov_b32 m0, s23
	v_lshl_add_u64 v[8:9], v[2:3], 0, s[6:7]
	s_add_i32 s22, s21, 0x4000
	s_mov_b32 s23, m0
	s_mov_b32 m0, s22
	s_nop 0
	global_load_lds_dwordx4 v[8:9], off
	s_mov_b32 m0, s23
	v_lshl_add_u64 v[8:9], v[4:5], 0, s[6:7]
	s_add_i32 s22, s21, 0xc000
	s_mov_b32 s23, m0
	s_mov_b32 m0, s22
	s_nop 0
	global_load_lds_dwordx4 v[8:9], off
	s_mov_b32 m0, s23
	v_lshl_add_u64 v[2:3], v[2:3], 0, s[8:9]
	s_add_i32 s22, s21, 0x6000
	s_mov_b32 s23, m0
	s_mov_b32 m0, s22
	s_nop 0
	global_load_lds_dwordx4 v[2:3], off
	s_mov_b32 m0, s23
	v_lshl_add_u64 v[2:3], v[4:5], 0, s[8:9]
	v_and_b32_e32 v145, 15, v144
	s_add_i32 s21, s21, 0xe000
	s_mov_b32 s22, m0
	s_mov_b32 m0, s21
	s_nop 0
	global_load_lds_dwordx4 v[2:3], off
	s_mov_b32 m0, s22
	v_ashrrev_i32_e32 v2, 1, v144
	v_and_or_b32 v148, v2, s18, v145
	v_lshlrev_b32_e32 v2, 7, v144
	v_lshrrev_b32_e32 v146, 4, v144
	v_bfe_u32 v147, v144, 4, 2
	v_and_b32_e32 v153, 0x6780, v2
	v_and_b32_e32 v2, 7, v144
	v_bitop3_b32 v3, v146, v2, 3 bitop3:0x6c
	v_bitop3_b32 v2, v147, v2, 4 bitop3:0x36
	v_bitop3_b32 v4, v10, 7, v144 bitop3:0x48
	v_lshlrev_b32_e32 v152, 4, v3
	v_lshlrev_b32_e32 v149, 4, v2
	v_mad_i64_i32 v[2:3], s[22:23], s14, v1, v[6:7]
	v_lshlrev_b32_e32 v4, 4, v4
	v_or_b32_e32 v2, v2, v4
	v_lshl_add_u64 v[140:141], v[134:135], 0, v[2:3]
	v_mad_i64_i32 v[2:3], s[22:23], s15, v1, v[6:7]
	v_or_b32_e32 v2, v2, v4
	s_mul_hi_i32 s13, s14, 0x108000
	s_mul_i32 s12, s14, 0x108000
	v_lshlrev_b32_e32 v151, 7, v148
	v_lshl_add_u64 v[142:143], v[136:137], 0, v[2:3]
	s_mov_b32 s21, 0
	v_mov_b32_e32 v38, v139
	v_mov_b32_e32 v39, v139
	v_mov_b32_e32 v40, v139
	v_mov_b32_e32 v41, v139
	v_mov_b32_e32 v2, v139
	v_mov_b32_e32 v3, v139
	v_mov_b32_e32 v4, v139
	v_mov_b32_e32 v5, v139
	v_mov_b32_e32 v6, v139
	v_mov_b32_e32 v7, v139
	v_mov_b32_e32 v8, v139
	v_mov_b32_e32 v9, v139
	v_mov_b32_e32 v10, v139
	v_mov_b32_e32 v11, v139
	v_mov_b32_e32 v12, v139
	v_mov_b32_e32 v13, v139
	v_mov_b32_e32 v14, v139
	v_mov_b32_e32 v15, v139
	v_mov_b32_e32 v16, v139
	v_mov_b32_e32 v17, v139
	v_mov_b32_e32 v18, v139
	v_mov_b32_e32 v19, v139
	v_mov_b32_e32 v20, v139
	v_mov_b32_e32 v21, v139
	v_mov_b32_e32 v22, v139
	v_mov_b32_e32 v23, v139
	v_mov_b32_e32 v24, v139
	v_mov_b32_e32 v25, v139
	v_mov_b32_e32 v26, v139
	v_mov_b32_e32 v27, v139
	v_mov_b32_e32 v28, v139
	v_mov_b32_e32 v29, v139
	v_mov_b32_e32 v30, v139
	v_mov_b32_e32 v31, v139
	v_mov_b32_e32 v32, v139
	v_mov_b32_e32 v33, v139
	v_mov_b32_e32 v34, v139
	v_mov_b32_e32 v35, v139
	v_mov_b32_e32 v36, v139
	v_mov_b32_e32 v37, v139
	v_mov_b32_e32 v42, v139
	v_mov_b32_e32 v43, v139
	v_mov_b32_e32 v44, v139
	v_mov_b32_e32 v45, v139
	v_mov_b32_e32 v46, v139
	v_mov_b32_e32 v47, v139
	v_mov_b32_e32 v48, v139
	v_mov_b32_e32 v49, v139
	v_mov_b32_e32 v50, v139
	v_mov_b32_e32 v51, v139
	v_mov_b32_e32 v52, v139
	v_mov_b32_e32 v53, v139
	v_mov_b32_e32 v54, v139
	v_mov_b32_e32 v55, v139
	v_mov_b32_e32 v56, v139
	v_mov_b32_e32 v57, v139
	v_mov_b32_e32 v58, v139
	v_mov_b32_e32 v59, v139
	v_mov_b32_e32 v60, v139
	v_mov_b32_e32 v61, v139
	v_mov_b32_e32 v62, v139
	v_mov_b32_e32 v63, v139
	v_mov_b32_e32 v64, v139
	v_mov_b32_e32 v65, v139
	v_mov_b32_e32 v66, v139
	v_mov_b32_e32 v67, v139
	v_mov_b32_e32 v68, v139
	v_mov_b32_e32 v69, v139
	v_mov_b32_e32 v70, v139
	v_mov_b32_e32 v71, v139
	v_mov_b32_e32 v72, v139
	v_mov_b32_e32 v73, v139
	v_mov_b32_e32 v74, v139
	v_mov_b32_e32 v75, v139
	v_mov_b32_e32 v76, v139
	v_mov_b32_e32 v77, v139
	v_mov_b32_e32 v78, v139
	v_mov_b32_e32 v79, v139
	v_mov_b32_e32 v80, v139
	v_mov_b32_e32 v81, v139
	v_mov_b32_e32 v82, v139
	v_mov_b32_e32 v83, v139
	v_mov_b32_e32 v84, v139
	v_mov_b32_e32 v85, v139
	v_mov_b32_e32 v86, v139
	v_mov_b32_e32 v87, v139
	v_mov_b32_e32 v88, v139
	v_mov_b32_e32 v89, v139
	v_mov_b32_e32 v90, v139
	v_mov_b32_e32 v91, v139
	v_mov_b32_e32 v92, v139
	v_mov_b32_e32 v93, v139
	v_mov_b32_e32 v94, v139
	v_mov_b32_e32 v95, v139
	v_mov_b32_e32 v96, v139
	v_mov_b32_e32 v97, v139
	v_mov_b32_e32 v98, v139
	v_mov_b32_e32 v99, v139
	v_mov_b32_e32 v100, v139
	v_mov_b32_e32 v101, v139
	v_mov_b32_e32 v102, v139
	v_mov_b32_e32 v103, v139
	v_mov_b32_e32 v104, v139
	v_mov_b32_e32 v105, v139
	v_mov_b32_e32 v106, v139
	v_mov_b32_e32 v107, v139
	v_mov_b32_e32 v108, v139
	v_mov_b32_e32 v109, v139
	v_mov_b32_e32 v110, v139
	v_mov_b32_e32 v111, v139
	v_mov_b32_e32 v112, v139
	v_mov_b32_e32 v113, v139
	v_mov_b32_e32 v114, v139
	v_mov_b32_e32 v115, v139
	v_mov_b32_e32 v116, v139
	v_mov_b32_e32 v117, v139
	v_mov_b32_e32 v118, v139
	v_mov_b32_e32 v119, v139
	v_mov_b32_e32 v120, v139
	v_mov_b32_e32 v121, v139
	v_mov_b32_e32 v122, v139
	v_mov_b32_e32 v123, v139
	v_mov_b32_e32 v124, v139
	v_mov_b32_e32 v125, v139
	v_mov_b32_e32 v126, v139
	v_mov_b32_e32 v127, v139
	v_mov_b32_e32 v128, v139
	v_mov_b32_e32 v129, v139
	v_readfirstlane_b32 s50, v0
	s_nop 3
	s_cmpk_lt_u32 s50, 0x100
	s_cbranch_scc1 .Lprio_skip2
	s_setprio 1
; #define GLDS_STAGE(st, kt_) do { \
;         _Pragma("unroll") for (int i_ = 0; i_ < FI; ++i_) { \
;             glds16(ap + (size_t)(32 * i_) * lda + (kt_) * 64, l3a + (st) + tid * 16 + i_ * 4096); \
;             glds16(bp + (size_t)(32 * i_) * ldb + (kt_) * 64, l3a + (st) + OPB + tid * 16 + i_ * 4096); } } while (0)
; #define GLDS_STAGE(st, kt_) do { \
;         _Pragma("unroll") for (int i_ = 0; i_ < 4; ++i_) { \
;             glds16(ap + (size_t)(64 * i_) * lda + (kt_) * 64, l3a + (st) + tid * 16 + i_ * 8192); \
;             glds16(bp + (size_t)(64 * i_) * ldb + (kt_) * 64, l3a + (st) + 32768 + tid * 16 + i_ * 8192); } } while (0)
; template <class Epi>
; DEV void gemm256_tile(const bf16_t* __restrict__ A, int lda, const bf16_t* __restrict__ Bt, int ldb, int K, unsigned char* lds, const Epi& epi) {
;     ...
;     for (int kt = 0; kt < nk; ++kt) {
;         const int cur = (kt & 1) * 65536;
;         asm volatile("s_waitcnt vmcnt(0)" ::: "memory");
;         __syncthreads();
;         if (kt + 1 < nk) GLDS_STAGE(cur ^ 65536, kt + 1);
; #pragma unroll
;         for (int kh = 0; kh < 2; ++kh) {
;             bf16x8 bfr[4];
;             const int ch = ((kh * 4 + fq) ^ sw) << 4;
; #pragma unroll
;             for (int i = 0; i < 4; ++i) bfr[i] = *(const bf16x8*)(lds + cur + boff + i * 2048 + ch);
; #pragma unroll
;             for (int mh = 0; mh < 2; ++mh) {
;                 bf16x8 af[4];
; #pragma unroll
;                 for (int i = 0; i < 4; ++i) af[i] = *(const bf16x8*)(lds + cur + aoff + (mh * 4 + i) * 2048 + ch);
; #pragma unroll
;                 for (int mi = 0; mi < 4; ++mi)
; #pragma unroll
;                     for (int ni = 0; ni < 4; ++ni) acc[mh * 4 + mi][ni] = __builtin_amdgcn_mfma_f32_16x16x32_bf16(bfr[ni], af[mi], acc[mh * 4 + mi][ni], 0, 0, 0);
;             }
;         }
;     }
.Lprio_skip2:
.LBB0_1236:
	s_and_b32 s48, s21, 0x10000
	s_xor_b32 s49, s48, 0x10000
	v_add_u32_e32 v216, s49, v138
	v_add_u32_e32 v217, s49, v150
	s_waitcnt vmcnt(0) lgkmcnt(0)
	s_barrier
	v_or_b32_e32 v248, s48, v153
	v_add_u32_e32 v249, s48, v151
	v_add_u32_e32 v244, v248, v152
	v_add_u32_e32 v245, v249, v152
	ds_read_b128 v[154:157], v244 offset:32768
	ds_read_b128 v[170:173], v244 offset:34816
	ds_read_b128 v[174:177], v244 offset:36864
	ds_read_b128 v[178:181], v244 offset:38912
	ds_read_b128 v[228:231], v245
	ds_read_b128 v[232:235], v245 offset:2048
	ds_read_b128 v[236:239], v245 offset:4096
	ds_read_b128 v[240:243], v245 offset:6144
	v_readfirstlane_b32 s40, v216
	v_readfirstlane_b32 s44, v217
	v_add_u32_e32 v246, v248, v149
	v_add_u32_e32 v247, v249, v149
	s_mov_b32 m0, s40
	v_lshl_add_u64 v[204:205], v[140:141], 0, s[4:5]
	global_load_lds_dwordx4 v[140:141], off
	s_mov_b32 m0, s44
	v_lshl_add_u64 v[210:211], v[142:143], 0, s[4:5]
	global_load_lds_dwordx4 v[142:143], off
	s_add_i32 s41, s40, 0x2000
	s_add_i32 s45, s44, 0x2000
	s_add_i32 s42, s40, 0x4000
	s_add_i32 s46, s44, 0x4000
	s_add_i32 s43, s40, 0x6000
	s_add_i32 s47, s44, 0x6000
	s_add_i32 s21, s21, 0x10000
	s_waitcnt lgkmcnt(3)
	v_mfma_f32_16x16x32_bf16 v[126:129], v[154:157], v[228:231], v[126:129]
	v_lshl_add_u64 v[206:207], v[140:141], 0, s[6:7]
	v_mfma_f32_16x16x32_bf16 v[122:125], v[170:173], v[228:231], v[122:125]
	v_lshl_add_u64 v[212:213], v[142:143], 0, s[6:7]
	v_mfma_f32_16x16x32_bf16 v[118:121], v[174:177], v[228:231], v[118:121]
	v_lshl_add_u64 v[208:209], v[140:141], 0, s[8:9]
	v_mfma_f32_16x16x32_bf16 v[114:117], v[178:181], v[228:231], v[114:117]
	v_lshl_add_u64 v[214:215], v[142:143], 0, s[8:9]
	s_waitcnt lgkmcnt(2)
	v_mfma_f32_16x16x32_bf16 v[110:113], v[154:157], v[232:235], v[110:113]
	v_mfma_f32_16x16x32_bf16 v[106:109], v[170:173], v[232:235], v[106:109]
	v_mfma_f32_16x16x32_bf16 v[102:105], v[174:177], v[232:235], v[102:105]
	v_mfma_f32_16x16x32_bf16 v[98:101], v[178:181], v[232:235], v[98:101]
	s_waitcnt lgkmcnt(1)
	v_mfma_f32_16x16x32_bf16 v[94:97], v[154:157], v[236:239], v[94:97]
	ds_read_b128 v[228:231], v245 offset:8192
	v_mfma_f32_16x16x32_bf16 v[90:93], v[170:173], v[236:239], v[90:93]
	ds_read_b128 v[232:235], v245 offset:10240
	v_mfma_f32_16x16x32_bf16 v[86:89], v[174:177], v[236:239], v[86:89]
	s_mov_b32 m0, s41
	v_mfma_f32_16x16x32_bf16 v[82:85], v[178:181], v[236:239], v[82:85]
	global_load_lds_dwordx4 v[204:205], off
	s_waitcnt lgkmcnt(2)
	v_mfma_f32_16x16x32_bf16 v[78:81], v[154:157], v[240:243], v[78:81]
	s_mov_b32 m0, s45
	v_mfma_f32_16x16x32_bf16 v[74:77], v[170:173], v[240:243], v[74:77]
	global_load_lds_dwordx4 v[210:211], off
	v_mfma_f32_16x16x32_bf16 v[70:73], v[174:177], v[240:243], v[70:73]
	v_mfma_f32_16x16x32_bf16 v[66:69], v[178:181], v[240:243], v[66:69]
	s_waitcnt lgkmcnt(1)
	v_mfma_f32_16x16x32_bf16 v[62:65], v[154:157], v[228:231], v[62:65]
	ds_read_b128 v[236:239], v245 offset:12288
	v_mfma_f32_16x16x32_bf16 v[58:61], v[170:173], v[228:231], v[58:61]
	ds_read_b128 v[240:243], v245 offset:14336
	v_mfma_f32_16x16x32_bf16 v[54:57], v[174:177], v[228:231], v[54:57]
	s_mov_b32 m0, s42
	v_mfma_f32_16x16x32_bf16 v[50:53], v[178:181], v[228:231], v[50:53]
	global_load_lds_dwordx4 v[206:207], off
	s_waitcnt lgkmcnt(2)
	v_mfma_f32_16x16x32_bf16 v[46:49], v[154:157], v[232:235], v[46:49]
	s_mov_b32 m0, s46
	v_mfma_f32_16x16x32_bf16 v[42:45], v[170:173], v[232:235], v[42:45]
	global_load_lds_dwordx4 v[212:213], off
	v_mfma_f32_16x16x32_bf16 v[34:37], v[174:177], v[232:235], v[34:37]
	v_mfma_f32_16x16x32_bf16 v[30:33], v[178:181], v[232:235], v[30:33]
	s_waitcnt lgkmcnt(1)
	v_mfma_f32_16x16x32_bf16 v[26:29], v[154:157], v[236:239], v[26:29]
	ds_read_b128 v[182:185], v246 offset:32768
	v_mfma_f32_16x16x32_bf16 v[22:25], v[170:173], v[236:239], v[22:25]
	ds_read_b128 v[186:189], v246 offset:34816
	v_mfma_f32_16x16x32_bf16 v[18:21], v[174:177], v[236:239], v[18:21]
	ds_read_b128 v[220:223], v246 offset:36864
	v_mfma_f32_16x16x32_bf16 v[14:17], v[178:181], v[236:239], v[14:17]
	ds_read_b128 v[224:227], v246 offset:38912
	s_waitcnt lgkmcnt(4)
	v_mfma_f32_16x16x32_bf16 v[10:13], v[154:157], v[240:243], v[10:13]
	ds_read_b128 v[228:231], v247
	v_mfma_f32_16x16x32_bf16 v[6:9], v[170:173], v[240:243], v[6:9]
	ds_read_b128 v[232:235], v247 offset:2048
	v_mfma_f32_16x16x32_bf16 v[2:5], v[174:177], v[240:243], v[2:5]
	s_mov_b32 m0, s43
	v_mfma_f32_16x16x32_bf16 v[38:41], v[178:181], v[240:243], v[38:41]
	global_load_lds_dwordx4 v[208:209], off
	s_mov_b32 m0, s47
	v_lshl_add_u64 v[140:141], v[140:141], 0, s[10:11]
	global_load_lds_dwordx4 v[214:215], off
	v_lshl_add_u64 v[142:143], v[142:143], 0, s[10:11]
	s_waitcnt lgkmcnt(1)
	v_mfma_f32_16x16x32_bf16 v[126:129], v[182:185], v[228:231], v[126:129]
	ds_read_b128 v[236:239], v247 offset:4096
	v_mfma_f32_16x16x32_bf16 v[122:125], v[186:189], v[228:231], v[122:125]
	ds_read_b128 v[240:243], v247 offset:6144
	v_mfma_f32_16x16x32_bf16 v[118:121], v[220:223], v[228:231], v[118:121]
	v_mfma_f32_16x16x32_bf16 v[114:117], v[224:227], v[228:231], v[114:117]
	s_waitcnt lgkmcnt(2)
	v_mfma_f32_16x16x32_bf16 v[110:113], v[182:185], v[232:235], v[110:113]
	v_mfma_f32_16x16x32_bf16 v[106:109], v[186:189], v[232:235], v[106:109]
	v_mfma_f32_16x16x32_bf16 v[102:105], v[220:223], v[232:235], v[102:105]
	v_mfma_f32_16x16x32_bf16 v[98:101], v[224:227], v[232:235], v[98:101]
	s_waitcnt lgkmcnt(1)
	v_mfma_f32_16x16x32_bf16 v[94:97], v[182:185], v[236:239], v[94:97]
	ds_read_b128 v[228:231], v247 offset:8192
	v_mfma_f32_16x16x32_bf16 v[90:93], v[186:189], v[236:239], v[90:93]
	ds_read_b128 v[232:235], v247 offset:10240
	v_mfma_f32_16x16x32_bf16 v[86:89], v[220:223], v[236:239], v[86:89]
	v_mfma_f32_16x16x32_bf16 v[82:85], v[224:227], v[236:239], v[82:85]
	s_waitcnt lgkmcnt(2)
; DEV unsigned cvt_pk_bf16(float lo, float hi) { const f32x2_t v = {lo, hi}; const bf16x2_t b = __builtin_convertvector(v, bf16x2_t); return __builtin_bit_cast(unsigned, b); }
; #define GLDS_STAGE(st, kt_) do { \
;         _Pragma("unroll") for (int i_ = 0; i_ < FI; ++i_) { \
;             glds16(ap + (size_t)(32 * i_) * lda + (kt_) * 64, l3a + (st) + tid * 16 + i_ * 4096); \
;             glds16(bp + (size_t)(32 * i_) * ldb + (kt_) * 64, l3a + (st) + OPB + tid * 16 + i_ * 4096); } } while (0)
; template <class Epi>
; DEV void gemm256_tile(const bf16_t* __restrict__ A, int lda, const bf16_t* __restrict__ Bt, int ldb, int K, unsigned char* lds, const Epi& epi) {
;     ...
;     for (int kt = 0; kt < nk; ++kt) {
;         const int cur = (kt & 1) * 65536;
;         asm volatile("s_waitcnt vmcnt(0)" ::: "memory");
;         __syncthreads();
;         if (kt + 1 < nk) GLDS_STAGE(cur ^ 65536, kt + 1);
; #pragma unroll
;         for (int kh = 0; kh < 2; ++kh) {
;             bf16x8 bfr[4];
;             const int ch = ((kh * 4 + fq) ^ sw) << 4;
; #pragma unroll
;             for (int i = 0; i < 4; ++i) bfr[i] = *(const bf16x8*)(lds + cur + boff + i * 2048 + ch);
; #pragma unroll
;             for (int mh = 0; mh < 2; ++mh) {
;                 bf16x8 af[4];
; #pragma unroll
;                 for (int i = 0; i < 4; ++i) af[i] = *(const bf16x8*)(lds + cur + aoff + (mh * 4 + i) * 2048 + ch);
; #pragma unroll
;                 for (int mi = 0; mi < 4; ++mi)
; #pragma unroll
;                     for (int ni = 0; ni < 4; ++ni) acc[mh * 4 + mi][ni] = __builtin_amdgcn_mfma_f32_16x16x32_bf16(bfr[ni], af[mi], acc[mh * 4 + mi][ni], 0, 0, 0);
;             }
;         }
;     }
;     ...
;     __syncthreads();
;     if constexpr (Epi::STAGE) {
; #pragma unroll
;         for (int mi = 0; mi < 8; ++mi)
; #pragma unroll
;             for (int ni = 0; ni < 4; ++ni) {
;                 const int row = wr * 128 + mi * 16 + fr, col = wc * 64 + ni * 16 + fq * 4;
;                 const f32x4 v = epi.xform(row, col, acc[mi][ni]);
;                 uint2 w; w.x = cvt_pk_bf16(v[0], v[1]); w.y = cvt_pk_bf16(v[2], v[3]);
;                 *(uint2*)(lds + row * 512 + ((((col >> 3) ^ (row & 31)) << 4) | (((col >> 2) & 1) << 3))) = w;
	v_mfma_f32_16x16x32_bf16 v[78:81], v[182:185], v[240:243], v[78:81]
	v_mfma_f32_16x16x32_bf16 v[74:77], v[186:189], v[240:243], v[74:77]
	v_mfma_f32_16x16x32_bf16 v[70:73], v[220:223], v[240:243], v[70:73]
	v_mfma_f32_16x16x32_bf16 v[66:69], v[224:227], v[240:243], v[66:69]
	s_waitcnt lgkmcnt(1)
	v_mfma_f32_16x16x32_bf16 v[62:65], v[182:185], v[228:231], v[62:65]
	ds_read_b128 v[236:239], v247 offset:12288
	v_mfma_f32_16x16x32_bf16 v[58:61], v[186:189], v[228:231], v[58:61]
	ds_read_b128 v[240:243], v247 offset:14336
	v_mfma_f32_16x16x32_bf16 v[54:57], v[220:223], v[228:231], v[54:57]
	v_mfma_f32_16x16x32_bf16 v[50:53], v[224:227], v[228:231], v[50:53]
	s_waitcnt lgkmcnt(2)
	v_mfma_f32_16x16x32_bf16 v[46:49], v[182:185], v[232:235], v[46:49]
	v_mfma_f32_16x16x32_bf16 v[42:45], v[186:189], v[232:235], v[42:45]
	v_mfma_f32_16x16x32_bf16 v[34:37], v[220:223], v[232:235], v[34:37]
	v_mfma_f32_16x16x32_bf16 v[30:33], v[224:227], v[232:235], v[30:33]
	s_waitcnt lgkmcnt(1)
	v_mfma_f32_16x16x32_bf16 v[26:29], v[182:185], v[236:239], v[26:29]
	v_mfma_f32_16x16x32_bf16 v[22:25], v[186:189], v[236:239], v[22:25]
	v_mfma_f32_16x16x32_bf16 v[18:21], v[220:223], v[236:239], v[18:21]
	v_mfma_f32_16x16x32_bf16 v[14:17], v[224:227], v[236:239], v[14:17]
	s_waitcnt lgkmcnt(0)
	v_mfma_f32_16x16x32_bf16 v[10:13], v[182:185], v[240:243], v[10:13]
	v_mfma_f32_16x16x32_bf16 v[6:9], v[186:189], v[240:243], v[6:9]
	v_mfma_f32_16x16x32_bf16 v[2:5], v[220:223], v[240:243], v[2:5]
	v_mfma_f32_16x16x32_bf16 v[38:41], v[224:227], v[240:243], v[38:41]
	s_cmp_eq_u32 s21, 0x1f0000
	s_cbranch_scc0 .LBB0_1236
	s_setprio 0
	v_or_b32_e32 v186, 0x18000, v153
	v_add_u32_e32 v202, 0x10000, v151
	v_add_u32_e32 v174, v186, v152
	v_add_u32_e32 v182, v202, v152
	s_waitcnt vmcnt(0)
	s_barrier
	ds_read_b128 v[140:143], v174
	ds_read_b128 v[154:157], v174 offset:2048
	ds_read_b128 v[150:153], v182
	ds_read_b128 v[170:173], v174 offset:4096
	ds_read_b128 v[174:177], v174 offset:6144
	s_waitcnt lgkmcnt(2)
	v_mfma_f32_16x16x32_bf16 v[126:129], v[140:143], v[150:153], v[126:129]
	s_sext_i32_i8 s14, s20
	s_lshl_b32 s20, s14, 8
	s_ashr_i32 s21, s20, 31
	v_mfma_f32_16x16x32_bf16 v[122:125], v[154:157], v[150:153], v[122:125]
	s_waitcnt lgkmcnt(1)
	v_mfma_f32_16x16x32_bf16 v[118:121], v[170:173], v[150:153], v[118:121]
	s_waitcnt lgkmcnt(0)
	v_mfma_f32_16x16x32_bf16 v[114:117], v[174:177], v[150:153], v[114:117]
	ds_read_b128 v[150:153], v182 offset:2048
	s_waitcnt lgkmcnt(0)
	v_mfma_f32_16x16x32_bf16 v[110:113], v[140:143], v[150:153], v[110:113]
	v_mfma_f32_16x16x32_bf16 v[106:109], v[154:157], v[150:153], v[106:109]
	v_mfma_f32_16x16x32_bf16 v[102:105], v[170:173], v[150:153], v[102:105]
	v_mfma_f32_16x16x32_bf16 v[98:101], v[174:177], v[150:153], v[98:101]
	ds_read_b128 v[150:153], v182 offset:4096
	s_waitcnt lgkmcnt(0)
	v_mfma_f32_16x16x32_bf16 v[94:97], v[140:143], v[150:153], v[94:97]
	v_mfma_f32_16x16x32_bf16 v[90:93], v[154:157], v[150:153], v[90:93]
	v_mfma_f32_16x16x32_bf16 v[86:89], v[170:173], v[150:153], v[86:89]
	v_mfma_f32_16x16x32_bf16 v[82:85], v[174:177], v[150:153], v[82:85]
	ds_read_b128 v[150:153], v182 offset:6144
	s_waitcnt lgkmcnt(0)
	v_mfma_f32_16x16x32_bf16 v[78:81], v[140:143], v[150:153], v[78:81]
	v_mfma_f32_16x16x32_bf16 v[74:77], v[154:157], v[150:153], v[74:77]
	v_mfma_f32_16x16x32_bf16 v[70:73], v[170:173], v[150:153], v[70:73]
	v_mfma_f32_16x16x32_bf16 v[66:69], v[174:177], v[150:153], v[66:69]
	ds_read_b128 v[150:153], v182 offset:8192
	ds_read_b128 v[178:181], v182 offset:10240
	s_waitcnt lgkmcnt(1)
	v_mfma_f32_16x16x32_bf16 v[62:65], v[140:143], v[150:153], v[62:65]
	v_mfma_f32_16x16x32_bf16 v[58:61], v[154:157], v[150:153], v[58:61]
	v_mfma_f32_16x16x32_bf16 v[54:57], v[170:173], v[150:153], v[54:57]
	v_mfma_f32_16x16x32_bf16 v[50:53], v[174:177], v[150:153], v[50:53]
	ds_read_b128 v[150:153], v182 offset:12288
	s_waitcnt lgkmcnt(1)
	v_mfma_f32_16x16x32_bf16 v[46:49], v[140:143], v[178:181], v[46:49]
	v_mfma_f32_16x16x32_bf16 v[42:45], v[154:157], v[178:181], v[42:45]
	v_mfma_f32_16x16x32_bf16 v[34:37], v[170:173], v[178:181], v[34:37]
	v_mfma_f32_16x16x32_bf16 v[30:33], v[174:177], v[178:181], v[30:33]
	ds_read_b128 v[178:181], v182 offset:14336
	s_waitcnt lgkmcnt(1)
	v_mfma_f32_16x16x32_bf16 v[182:185], v[140:143], v[150:153], v[26:29]
	s_nop 2
	v_add_u32_e32 v29, v186, v149
	ds_read_b128 v[186:189], v29
	ds_read_b128 v[190:193], v29 offset:2048
	ds_read_b128 v[194:197], v29 offset:4096
	ds_read_b128 v[198:201], v29 offset:6144
	v_add_u32_e32 v29, v202, v149
	v_mfma_f32_16x16x32_bf16 v[22:25], v[154:157], v[150:153], v[22:25]
	v_and_b32_e32 v28, 0xc0, v144
	v_lshl_or_b32 v147, v147, 2, v28
	v_lshlrev_b32_e32 v28, 3, v146
	v_mfma_f32_16x16x32_bf16 v[18:21], v[170:173], v[150:153], v[18:21]
	v_lshl_add_u64 v[26:27], v[132:133], 0, s[12:13]
	v_lshl_add_u64 v[26:27], s[20:21], 1, v[26:27]
	s_mov_b32 s12, 0
	v_mfma_f32_16x16x32_bf16 v[14:17], v[174:177], v[150:153], v[14:17]
	ds_read_b128 v[150:153], v29
	ds_read_b128 v[202:205], v29 offset:2048
	ds_read_b128 v[206:209], v29 offset:4096
	ds_read_b128 v[210:213], v29 offset:6144
	s_waitcnt lgkmcnt(3)
	v_mfma_f32_16x16x32_bf16 v[126:129], v[186:189], v[150:153], v[126:129]
	v_mfma_f32_16x16x32_bf16 v[122:125], v[190:193], v[150:153], v[122:125]
	s_waitcnt lgkmcnt(1)
	v_mfma_f32_16x16x32_bf16 v[94:97], v[186:189], v[206:209], v[94:97]
	v_mfma_f32_16x16x32_bf16 v[10:13], v[140:143], v[178:181], v[10:13]
	ds_read_b128 v[140:143], v29 offset:8192
	ds_read_b128 v[214:217], v29 offset:10240
	ds_read_b128 v[218:221], v29 offset:12288
	ds_read_b128 v[222:225], v29 offset:14336
	v_lshlrev_b32_e32 v29, 9, v148
	v_and_or_b32 v146, v28, 8, v29
	v_mfma_f32_16x16x32_bf16 v[118:121], v[194:197], v[150:153], v[118:121]
	v_cvt_pk_bf16_f32 v28, v126, v127
	v_lshrrev_b32_e32 v126, 3, v147
	v_xor_b32_e32 v127, v126, v145
	v_mfma_f32_16x16x32_bf16 v[90:93], v[190:193], v[206:209], v[90:93]
	v_cvt_pk_bf16_f32 v29, v128, v129
	v_lshl_or_b32 v127, v127, 4, v146
	v_cvt_pk_bf16_f32 v122, v122, v123
	v_mfma_f32_16x16x32_bf16 v[114:117], v[198:201], v[150:153], v[114:117]
	v_cvt_pk_bf16_f32 v123, v124, v125
	v_bitop3_b32 v124, v126, v145, 2 bitop3:0x36
	v_cvt_pk_bf16_f32 v94, v94, v95
	v_mfma_f32_16x16x32_bf16 v[86:89], v[194:197], v[206:209], v[86:89]
	v_cvt_pk_bf16_f32 v95, v96, v97
	s_waitcnt lgkmcnt(0)
	s_barrier
; DEV unsigned cvt_pk_bf16(float lo, float hi) { const f32x2_t v = {lo, hi}; const bf16x2_t b = __builtin_convertvector(v, bf16x2_t); return __builtin_bit_cast(unsigned, b); }
; template <class Epi>
; DEV void gemm256_tile(const bf16_t* __restrict__ A, int lda, const bf16_t* __restrict__ Bt, int ldb, int K, unsigned char* lds, const Epi& epi) {
;     ...
;     __syncthreads();
;     if constexpr (Epi::STAGE) {
; #pragma unroll
;         for (int mi = 0; mi < 8; ++mi)
; #pragma unroll
;             for (int ni = 0; ni < 4; ++ni) {
;                 const int row = wr * 128 + mi * 16 + fr, col = wc * 64 + ni * 16 + fq * 4;
;                 const f32x4 v = epi.xform(row, col, acc[mi][ni]);
;                 uint2 w; w.x = cvt_pk_bf16(v[0], v[1]); w.y = cvt_pk_bf16(v[2], v[3]);
;                 *(uint2*)(lds + row * 512 + ((((col >> 3) ^ (row & 31)) << 4) | (((col >> 2) & 1) << 3))) = w;
;             }
;         __syncthreads();
	v_mfma_f32_16x16x32_bf16 v[110:113], v[186:189], v[202:205], v[110:113]
	v_lshl_add_u32 v124, v124, 4, v146
	v_cvt_pk_bf16_f32 v118, v118, v119
	v_mfma_f32_16x16x32_bf16 v[82:85], v[198:201], v[206:209], v[82:85]
	v_cvt_pk_bf16_f32 v119, v120, v121
	v_bitop3_b32 v120, v126, v145, 4 bitop3:0x36
	ds_write2st64_b64 v127, v[28:29], v[94:95] offset1:32
	v_mfma_f32_16x16x32_bf16 v[106:109], v[190:193], v[202:205], v[106:109]
	v_cvt_pk_bf16_f32 v28, v90, v91
	v_cvt_pk_bf16_f32 v29, v92, v93
	v_lshl_add_u32 v120, v120, 4, v146
	v_mfma_f32_16x16x32_bf16 v[78:81], v[186:189], v[210:213], v[78:81]
	v_cvt_pk_bf16_f32 v114, v114, v115
	v_cvt_pk_bf16_f32 v115, v116, v117
	v_bitop3_b32 v116, v126, v145, 6 bitop3:0x36
	v_mfma_f32_16x16x32_bf16 v[102:105], v[194:197], v[202:205], v[102:105]
	ds_write2st64_b64 v124, v[122:123], v[28:29] offset1:32
	v_cvt_pk_bf16_f32 v28, v86, v87
	v_cvt_pk_bf16_f32 v29, v88, v89
	v_mfma_f32_16x16x32_bf16 v[74:77], v[190:193], v[210:213], v[74:77]
	v_lshl_add_u32 v116, v116, 4, v146
	v_or_b32_e32 v117, 16, v145
	v_cvt_pk_bf16_f32 v110, v110, v111
	v_mfma_f32_16x16x32_bf16 v[2:5], v[170:173], v[178:181], v[2:5]
	v_cvt_pk_bf16_f32 v111, v112, v113
	v_bitop3_b32 v112, v126, v145, 16 bitop3:0x1e
	ds_write2st64_b64 v120, v[118:119], v[28:29] offset1:32
	v_mfma_f32_16x16x32_bf16 v[98:101], v[198:201], v[202:205], v[98:101]
	v_cvt_pk_bf16_f32 v28, v82, v83
	v_cvt_pk_bf16_f32 v29, v84, v85
	v_lshl_or_b32 v112, v112, 4, v146
	v_mfma_f32_16x16x32_bf16 v[70:73], v[194:197], v[210:213], v[70:73]
	v_cvt_pk_bf16_f32 v106, v106, v107
	v_cvt_pk_bf16_f32 v107, v108, v109
	v_bitop3_b32 v108, v126, v117, 2 bitop3:0x36
	v_mfma_f32_16x16x32_bf16 v[66:69], v[198:201], v[210:213], v[66:69]
	ds_write2st64_b64 v116, v[114:115], v[28:29] offset1:32
	v_cvt_pk_bf16_f32 v28, v78, v79
	v_cvt_pk_bf16_f32 v29, v80, v81
	v_lshl_add_u32 v108, v108, 4, v146
	v_cvt_pk_bf16_f32 v102, v102, v103
	v_cvt_pk_bf16_f32 v103, v104, v105
	v_bitop3_b32 v104, v126, v117, 4 bitop3:0x36
	ds_write2st64_b64 v112, v[110:111], v[28:29] offset0:16 offset1:48
	v_cvt_pk_bf16_f32 v28, v74, v75
	v_cvt_pk_bf16_f32 v29, v76, v77
	v_lshl_add_u32 v104, v104, 4, v146
	v_cvt_pk_bf16_f32 v98, v98, v99
	v_cvt_pk_bf16_f32 v99, v100, v101
	v_bitop3_b32 v100, v126, v117, 6 bitop3:0x36
	ds_write2st64_b64 v108, v[106:107], v[28:29] offset0:16 offset1:48
	v_cvt_pk_bf16_f32 v28, v70, v71
	v_cvt_pk_bf16_f32 v29, v72, v73
	v_mfma_f32_16x16x32_bf16 v[34:37], v[194:197], v[214:217], v[34:37]
	v_lshl_add_u32 v100, v100, 4, v146
	ds_write2st64_b64 v104, v[102:103], v[28:29] offset0:16 offset1:48
	v_cvt_pk_bf16_f32 v28, v66, v67
	v_mfma_f32_16x16x32_bf16 v[2:5], v[194:197], v[222:225], v[2:5]
	v_cvt_pk_bf16_f32 v29, v68, v69
	ds_write2st64_b64 v100, v[98:99], v[28:29] offset0:16 offset1:48
	s_nop 1
	v_cvt_pk_bf16_f32 v34, v34, v35
	v_mfma_f32_16x16x32_bf16 v[38:41], v[174:177], v[178:181], v[38:41]
	v_cvt_pk_bf16_f32 v35, v36, v37
	s_nop 0
	v_cvt_pk_bf16_f32 v2, v2, v3
	v_cvt_pk_bf16_f32 v3, v4, v5
	v_mfma_f32_16x16x32_bf16 v[6:9], v[154:157], v[178:181], v[6:9]
	ds_write2st64_b64 v104, v[34:35], v[2:3] offset0:80 offset1:112
	v_mfma_f32_16x16x32_bf16 v[28:31], v[198:201], v[214:217], v[30:33]
	v_mfma_f32_16x16x32_bf16 v[2:5], v[198:201], v[222:225], v[38:41]
	v_mfma_f32_16x16x32_bf16 v[62:65], v[186:189], v[140:143], v[62:65]
	s_nop 5
	v_cvt_pk_bf16_f32 v32, v28, v29
	v_cvt_pk_bf16_f32 v33, v30, v31
	v_cvt_pk_bf16_f32 v2, v2, v3
	v_mfma_f32_16x16x32_bf16 v[58:61], v[190:193], v[140:143], v[58:61]
	v_cvt_pk_bf16_f32 v3, v4, v5
	v_cvt_pk_bf16_f32 v62, v62, v63
	v_cvt_pk_bf16_f32 v63, v64, v65
	v_mfma_f32_16x16x32_bf16 v[54:57], v[194:197], v[140:143], v[54:57]
	ds_write2st64_b64 v100, v[32:33], v[2:3] offset0:80 offset1:112
	s_nop 2
	v_cvt_pk_bf16_f32 v58, v58, v59
	v_cvt_pk_bf16_f32 v59, v60, v61
	v_mfma_f32_16x16x32_bf16 v[50:53], v[198:201], v[140:143], v[50:53]
	v_and_b32_e32 v2, 0x1f0, v138
	v_cvt_pk_bf16_f32 v54, v54, v55
	v_cvt_pk_bf16_f32 v55, v56, v57
	v_mfma_f32_16x16x32_bf16 v[46:49], v[186:189], v[214:217], v[46:49]
	v_mfma_f32_16x16x32_bf16 v[42:45], v[190:193], v[214:217], v[42:45]
	s_nop 2
	v_cvt_pk_bf16_f32 v50, v50, v51
	v_cvt_pk_bf16_f32 v51, v52, v53
	s_nop 1
	v_cvt_pk_bf16_f32 v46, v46, v47
	v_mfma_f32_16x16x32_bf16 v[28:31], v[186:189], v[218:221], v[182:185]
	v_cvt_pk_bf16_f32 v47, v48, v49
	v_cvt_pk_bf16_f32 v42, v42, v43
	v_cvt_pk_bf16_f32 v43, v44, v45
	v_mfma_f32_16x16x32_bf16 v[22:25], v[190:193], v[218:221], v[22:25]
	v_mfma_f32_16x16x32_bf16 v[18:21], v[194:197], v[218:221], v[18:21]
	s_nop 2
	v_cvt_pk_bf16_f32 v28, v28, v29
	v_cvt_pk_bf16_f32 v29, v30, v31
	s_nop 1
	v_cvt_pk_bf16_f32 v22, v22, v23
	v_mfma_f32_16x16x32_bf16 v[14:17], v[198:201], v[218:221], v[14:17]
	v_cvt_pk_bf16_f32 v23, v24, v25
	v_cvt_pk_bf16_f32 v18, v18, v19
	v_cvt_pk_bf16_f32 v19, v20, v21
	v_mfma_f32_16x16x32_bf16 v[10:13], v[186:189], v[222:225], v[10:13]
	ds_write2st64_b64 v127, v[62:63], v[28:29] offset0:64 offset1:96
	s_nop 2
	v_cvt_pk_bf16_f32 v14, v14, v15
	v_cvt_pk_bf16_f32 v15, v16, v17
	v_mfma_f32_16x16x32_bf16 v[6:9], v[190:193], v[222:225], v[6:9]
	ds_write2st64_b64 v124, v[58:59], v[22:23] offset0:64 offset1:96
	v_cvt_pk_bf16_f32 v10, v10, v11
	v_cvt_pk_bf16_f32 v11, v12, v13
	ds_write2st64_b64 v120, v[54:55], v[18:19] offset0:64 offset1:96
	ds_write2st64_b64 v116, v[50:51], v[14:15] offset0:64 offset1:96
	s_nop 2
	v_cvt_pk_bf16_f32 v6, v6, v7
	v_cvt_pk_bf16_f32 v7, v8, v9
	ds_write2st64_b64 v112, v[46:47], v[10:11] offset0:80 offset1:112
	ds_write2st64_b64 v108, v[42:43], v[6:7] offset0:80 offset1:112
	s_waitcnt lgkmcnt(0)
	s_barrier

; #define LAS __attribute__((address_space(3)))
; #define GLDS_STAGE(st, kt_) do { \
;         _Pragma("unroll") for (int i_ = 0; i_ < FI; ++i_) { \
;             glds16(ap + (size_t)(32 * i_) * lda + (kt_) * 64, l3a + (st) + tid * 16 + i_ * 4096); \
;             glds16(bp + (size_t)(32 * i_) * ldb + (kt_) * 64, l3a + (st) + OPB + tid * 16 + i_ * 4096); } } while (0)
; #define GLDS_STAGE(st, kt_) do { \
;         _Pragma("unroll") for (int i_ = 0; i_ < 4; ++i_) { \
;             glds16(ap + (size_t)(64 * i_) * lda + (kt_) * 64, l3a + (st) + tid * 16 + i_ * 8192); \
;             glds16(bp + (size_t)(64 * i_) * ldb + (kt_) * 64, l3a + (st) + 32768 + tid * 16 + i_ * 8192); } } while (0)
; template <class Epi>
; DEV void gemm256_tile(const bf16_t* __restrict__ A, int lda, const bf16_t* __restrict__ Bt, int ldb, int K, unsigned char* lds, const Epi& epi) {
;     int tid = threadIdx.x; asm volatile("" : "+v"(tid)); const int lane = tid & 63, wid = tid >> 6;
;     const int wr = wid >> 2, wc = wid & 3, fr = lane & 15, fq = lane >> 4;
;     f32x4 acc[8][4];
; #pragma unroll
;     for (int i = 0; i < 8; ++i)
; #pragma unroll
;         for (int j = 0; j < 4; ++j) acc[i][j] = (f32x4){0.f, 0.f, 0.f, 0.f};
;     const int lrow = tid >> 3, lcs = (tid & 7) ^ (lrow & 7);
;     const bf16_t* ap = A + (size_t)lrow * lda + lcs * 8;
;     const bf16_t* bp = Bt + (size_t)lrow * ldb + lcs * 8;
;     const unsigned l3a = (unsigned)(size_t)(LAS unsigned char*)lds;
;     const int nk = K >> 6;
;     ...
;     GLDS_STAGE(0, 0);
;     const int aoff = (wr * 128 + fr) * 128, boff = 32768 + (wc * 64 + fr) * 128, sw = fr & 7;
.LBB0_1465:
	s_lshl_b32 s12, s19, 5
	s_and_b32 s12, s12, 0xe0
	s_ashr_i32 s13, s19, 3
	s_add_i32 s12, s12, s13
	s_ashr_i32 s13, s12, 31
	s_lshr_b32 s13, s13, 26
	s_add_i32 s13, s12, s13
	s_ashr_i32 s14, s13, 6
	s_and_b32 s13, s13, 0xffc0
	s_sub_i32 s12, s12, s13
	s_bfe_i32 s13, s12, 0x80000
	s_bfe_u32 s13, s13, 0x3000c
	s_add_i32 s13, s12, s13
	s_bfe_i32 s15, s13, 0x80000
	s_and_b32 s13, s13, 0xf8
	s_sub_i32 s12, s12, s13
	v_mov_b32_e32 v146, v0
	s_lshl_b32 s14, s14, 3
	s_sext_i32_i16 s15, s15
	s_sext_i32_i8 s12, s12
	s_lshr_b32 s20, s15, 3
	v_ashrrev_i32_e32 v10, 3, v146
	s_add_i32 s14, s14, s12
	s_ashr_i32 s15, s15, 3
	v_xor_b32_e32 v8, v10, v146
	v_mad_i64_i32 v[2:3], s[22:23], s14, v1, v[132:133]
	v_mad_i64_i32 v[4:5], s[22:23], s15, v1, v[160:161]
	v_lshlrev_b32_e32 v8, 4, v8
	v_mad_i64_i32 v[2:3], s[22:23], v10, s17, v[2:3]
	v_and_b32_e32 v140, 0x70, v8
	v_mad_i64_i32 v[4:5], s[22:23], v10, s17, v[4:5]
	v_lshl_add_u64 v[2:3], v[2:3], 0, v[140:141]
	v_lshl_add_u64 v[4:5], v[4:5], 0, v[140:141]
	v_lshlrev_b32_e32 v140, 4, v146
	v_mad_i64_i32 v[6:7], s[22:23], v10, s17, 0
	v_add_u32_e32 v153, 0x8000, v140
	v_readfirstlane_b32 s21, v140
	s_mov_b32 s22, m0
	s_mov_b32 m0, s21
	s_nop 0
	global_load_lds_dwordx4 v[2:3], off
	s_mov_b32 m0, s22
	v_lshl_add_u64 v[8:9], v[2:3], 0, s[4:5]
	v_readfirstlane_b32 s22, v153
	s_mov_b32 s23, m0
	s_mov_b32 m0, s22
	s_nop 0
	global_load_lds_dwordx4 v[4:5], off
	s_mov_b32 m0, s23
	s_add_i32 s22, s21, 0x2000
	s_mov_b32 s23, m0
	s_mov_b32 m0, s22
	s_nop 0
	global_load_lds_dwordx4 v[8:9], off
	s_mov_b32 m0, s23
	v_lshl_add_u64 v[8:9], v[4:5], 0, s[4:5]
	s_add_i32 s22, s21, 0xa000
	s_mov_b32 s23, m0
	s_mov_b32 m0, s22
	s_nop 0
	global_load_lds_dwordx4 v[8:9], off
	s_mov_b32 m0, s23
	v_lshl_add_u64 v[8:9], v[2:3], 0, s[6:7]
	s_add_i32 s22, s21, 0x4000
	s_mov_b32 s23, m0
	s_mov_b32 m0, s22
	s_nop 0
	global_load_lds_dwordx4 v[8:9], off
	s_mov_b32 m0, s23
	v_lshl_add_u64 v[8:9], v[4:5], 0, s[6:7]
	s_add_i32 s22, s21, 0xc000
	s_mov_b32 s23, m0
	s_mov_b32 m0, s22
	s_nop 0
	global_load_lds_dwordx4 v[8:9], off
	s_mov_b32 m0, s23
	v_lshl_add_u64 v[2:3], v[2:3], 0, s[8:9]
	s_add_i32 s22, s21, 0x6000
	s_mov_b32 s23, m0
	s_mov_b32 m0, s22
	s_nop 0
	global_load_lds_dwordx4 v[2:3], off
	s_mov_b32 m0, s23
	v_lshl_add_u64 v[2:3], v[4:5], 0, s[8:9]
	v_and_b32_e32 v147, 15, v146
	s_add_i32 s21, s21, 0xe000
	s_mov_b32 s22, m0
	s_mov_b32 m0, s21
	s_nop 0
	global_load_lds_dwordx4 v[2:3], off
	s_mov_b32 m0, s22
	v_ashrrev_i32_e32 v2, 1, v146
	v_and_or_b32 v150, v2, s18, v147
	v_lshlrev_b32_e32 v2, 7, v146
	v_lshrrev_b32_e32 v148, 4, v146
	v_bfe_u32 v149, v146, 4, 2
	v_and_b32_e32 v155, 0x6780, v2
	v_and_b32_e32 v2, 7, v146
	v_bitop3_b32 v3, v148, v2, 3 bitop3:0x6c
	v_bitop3_b32 v2, v149, v2, 4 bitop3:0x36
	v_bitop3_b32 v4, v10, 7, v146 bitop3:0x48
	v_lshlrev_b32_e32 v154, 4, v3
	v_lshlrev_b32_e32 v151, 4, v2
	v_mad_i64_i32 v[2:3], s[22:23], s14, v1, v[6:7]
	v_lshlrev_b32_e32 v4, 4, v4
	v_or_b32_e32 v2, v2, v4
	v_lshl_add_u64 v[142:143], v[136:137], 0, v[2:3]
	v_mad_i64_i32 v[2:3], s[22:23], s15, v1, v[6:7]
	v_or_b32_e32 v2, v2, v4
	s_mul_hi_i32 s13, s14, 0x108000
	s_mul_i32 s12, s14, 0x108000
	v_lshlrev_b32_e32 v152, 7, v150
	v_lshl_add_u64 v[144:145], v[138:139], 0, v[2:3]
	s_mov_b32 s21, 0
	v_mov_b32_e32 v38, v141
	v_mov_b32_e32 v39, v141
	v_mov_b32_e32 v40, v141
	v_mov_b32_e32 v41, v141
	v_mov_b32_e32 v2, v141
	v_mov_b32_e32 v3, v141
	v_mov_b32_e32 v4, v141
	v_mov_b32_e32 v5, v141
	v_mov_b32_e32 v6, v141
	v_mov_b32_e32 v7, v141
	v_mov_b32_e32 v8, v141
	v_mov_b32_e32 v9, v141
	v_mov_b32_e32 v10, v141
	v_mov_b32_e32 v11, v141
	v_mov_b32_e32 v12, v141
	v_mov_b32_e32 v13, v141
	v_mov_b32_e32 v14, v141
	v_mov_b32_e32 v15, v141
	v_mov_b32_e32 v16, v141
	v_mov_b32_e32 v17, v141
	v_mov_b32_e32 v18, v141
	v_mov_b32_e32 v19, v141
	v_mov_b32_e32 v20, v141
	v_mov_b32_e32 v21, v141
	v_mov_b32_e32 v22, v141
	v_mov_b32_e32 v23, v141
	v_mov_b32_e32 v24, v141
	v_mov_b32_e32 v25, v141
	v_mov_b32_e32 v26, v141
	v_mov_b32_e32 v27, v141
	v_mov_b32_e32 v28, v141
	v_mov_b32_e32 v29, v141
	v_mov_b32_e32 v30, v141
	v_mov_b32_e32 v31, v141
	v_mov_b32_e32 v32, v141
	v_mov_b32_e32 v33, v141
	v_mov_b32_e32 v34, v141
	v_mov_b32_e32 v35, v141
	v_mov_b32_e32 v36, v141
	v_mov_b32_e32 v37, v141
	v_mov_b32_e32 v42, v141
	v_mov_b32_e32 v43, v141
	v_mov_b32_e32 v44, v141
	v_mov_b32_e32 v45, v141
	v_mov_b32_e32 v46, v141
	v_mov_b32_e32 v47, v141
	v_mov_b32_e32 v48, v141
	v_mov_b32_e32 v49, v141
	v_mov_b32_e32 v50, v141
	v_mov_b32_e32 v51, v141
	v_mov_b32_e32 v52, v141
	v_mov_b32_e32 v53, v141
	v_mov_b32_e32 v54, v141
	v_mov_b32_e32 v55, v141
	v_mov_b32_e32 v56, v141
	v_mov_b32_e32 v57, v141
	v_mov_b32_e32 v58, v141
	v_mov_b32_e32 v59, v141
	v_mov_b32_e32 v60, v141
	v_mov_b32_e32 v61, v141
	v_mov_b32_e32 v62, v141
	v_mov_b32_e32 v63, v141
	v_mov_b32_e32 v64, v141
	v_mov_b32_e32 v65, v141
	v_mov_b32_e32 v66, v141
	v_mov_b32_e32 v67, v141
	v_mov_b32_e32 v68, v141
	v_mov_b32_e32 v69, v141
	v_mov_b32_e32 v70, v141
	v_mov_b32_e32 v71, v141
	v_mov_b32_e32 v72, v141
	v_mov_b32_e32 v73, v141
	v_mov_b32_e32 v74, v141
	v_mov_b32_e32 v75, v141
	v_mov_b32_e32 v76, v141
	v_mov_b32_e32 v77, v141
	v_mov_b32_e32 v78, v141
	v_mov_b32_e32 v79, v141
	v_mov_b32_e32 v80, v141
	v_mov_b32_e32 v81, v141
	v_mov_b32_e32 v82, v141
	v_mov_b32_e32 v83, v141
	v_mov_b32_e32 v84, v141
	v_mov_b32_e32 v85, v141
	v_mov_b32_e32 v86, v141
	v_mov_b32_e32 v87, v141
	v_mov_b32_e32 v88, v141
	v_mov_b32_e32 v89, v141
	v_mov_b32_e32 v90, v141
	v_mov_b32_e32 v91, v141
	v_mov_b32_e32 v92, v141
	v_mov_b32_e32 v93, v141
	v_mov_b32_e32 v94, v141
	v_mov_b32_e32 v95, v141
	v_mov_b32_e32 v96, v141
	v_mov_b32_e32 v97, v141
	v_mov_b32_e32 v98, v141
	v_mov_b32_e32 v99, v141
	v_mov_b32_e32 v100, v141
	v_mov_b32_e32 v101, v141
	v_mov_b32_e32 v102, v141
	v_mov_b32_e32 v103, v141
	v_mov_b32_e32 v104, v141
	v_mov_b32_e32 v105, v141
	v_mov_b32_e32 v106, v141
	v_mov_b32_e32 v107, v141
	v_mov_b32_e32 v108, v141
	v_mov_b32_e32 v109, v141
	v_mov_b32_e32 v110, v141
	v_mov_b32_e32 v111, v141
	v_mov_b32_e32 v112, v141
	v_mov_b32_e32 v113, v141
	v_mov_b32_e32 v114, v141
	v_mov_b32_e32 v115, v141
	v_mov_b32_e32 v116, v141
	v_mov_b32_e32 v117, v141
	v_mov_b32_e32 v118, v141
	v_mov_b32_e32 v119, v141
	v_mov_b32_e32 v120, v141
	v_mov_b32_e32 v121, v141
	v_mov_b32_e32 v122, v141
	v_mov_b32_e32 v123, v141
	v_mov_b32_e32 v124, v141
	v_mov_b32_e32 v125, v141
	v_mov_b32_e32 v126, v141
	v_mov_b32_e32 v127, v141
	v_mov_b32_e32 v128, v141
	v_mov_b32_e32 v129, v141
	v_readfirstlane_b32 s50, v0
	s_nop 3
	s_cmpk_lt_u32 s50, 0x100
	s_cbranch_scc1 .Lprio_skip3
	s_setprio 1
; #define GLDS_STAGE(st, kt_) do { \
;         _Pragma("unroll") for (int i_ = 0; i_ < FI; ++i_) { \
;             glds16(ap + (size_t)(32 * i_) * lda + (kt_) * 64, l3a + (st) + tid * 16 + i_ * 4096); \
;             glds16(bp + (size_t)(32 * i_) * ldb + (kt_) * 64, l3a + (st) + OPB + tid * 16 + i_ * 4096); } } while (0)
; #define GLDS_STAGE(st, kt_) do { \
;         _Pragma("unroll") for (int i_ = 0; i_ < 4; ++i_) { \
;             glds16(ap + (size_t)(64 * i_) * lda + (kt_) * 64, l3a + (st) + tid * 16 + i_ * 8192); \
;             glds16(bp + (size_t)(64 * i_) * ldb + (kt_) * 64, l3a + (st) + 32768 + tid * 16 + i_ * 8192); } } while (0)
; template <class Epi>
; DEV void gemm256_tile(const bf16_t* __restrict__ A, int lda, const bf16_t* __restrict__ Bt, int ldb, int K, unsigned char* lds, const Epi& epi) {
;     ...
;     for (int kt = 0; kt < nk; ++kt) {
;         const int cur = (kt & 1) * 65536;
;         asm volatile("s_waitcnt vmcnt(0)" ::: "memory");
;         __syncthreads();
;         if (kt + 1 < nk) GLDS_STAGE(cur ^ 65536, kt + 1);
; #pragma unroll
;         for (int kh = 0; kh < 2; ++kh) {
;             bf16x8 bfr[4];
;             const int ch = ((kh * 4 + fq) ^ sw) << 4;
; #pragma unroll
;             for (int i = 0; i < 4; ++i) bfr[i] = *(const bf16x8*)(lds + cur + boff + i * 2048 + ch);
; #pragma unroll
;             for (int mh = 0; mh < 2; ++mh) {
;                 bf16x8 af[4];
; #pragma unroll
;                 for (int i = 0; i < 4; ++i) af[i] = *(const bf16x8*)(lds + cur + aoff + (mh * 4 + i) * 2048 + ch);
; #pragma unroll
;                 for (int mi = 0; mi < 4; ++mi)
; #pragma unroll
;                     for (int ni = 0; ni < 4; ++ni) acc[mh * 4 + mi][ni] = __builtin_amdgcn_mfma_f32_16x16x32_bf16(bfr[ni], af[mi], acc[mh * 4 + mi][ni], 0, 0, 0);
;             }
;         }
;     }
.Lprio_skip3:
.LBB0_1466:
	s_and_b32 s48, s21, 0x10000
	s_xor_b32 s49, s48, 0x10000
	v_add_u32_e32 v216, s49, v140
	v_add_u32_e32 v217, s49, v153
	s_waitcnt vmcnt(0) lgkmcnt(0)
	s_barrier
	v_or_b32_e32 v248, s48, v155
	v_add_u32_e32 v249, s48, v152
	v_add_u32_e32 v244, v248, v154
	v_add_u32_e32 v245, v249, v154
	ds_read_b128 v[162:165], v244 offset:32768
	ds_read_b128 v[166:169], v244 offset:34816
	ds_read_b128 v[170:173], v244 offset:36864
	ds_read_b128 v[174:177], v244 offset:38912
	ds_read_b128 v[228:231], v245
	ds_read_b128 v[232:235], v245 offset:2048
	ds_read_b128 v[236:239], v245 offset:4096
	ds_read_b128 v[240:243], v245 offset:6144
	v_readfirstlane_b32 s40, v216
	v_readfirstlane_b32 s44, v217
	v_add_u32_e32 v246, v248, v151
	v_add_u32_e32 v247, v249, v151
	s_mov_b32 m0, s40
	v_lshl_add_u64 v[204:205], v[142:143], 0, s[4:5]
	global_load_lds_dwordx4 v[142:143], off
	s_mov_b32 m0, s44
	v_lshl_add_u64 v[210:211], v[144:145], 0, s[4:5]
	global_load_lds_dwordx4 v[144:145], off
	s_add_i32 s41, s40, 0x2000
	s_add_i32 s45, s44, 0x2000
	s_add_i32 s42, s40, 0x4000
	s_add_i32 s46, s44, 0x4000
	s_add_i32 s43, s40, 0x6000
	s_add_i32 s47, s44, 0x6000
	s_add_i32 s21, s21, 0x10000
	s_waitcnt lgkmcnt(3)
	v_mfma_f32_16x16x32_bf16 v[126:129], v[162:165], v[228:231], v[126:129]
	v_lshl_add_u64 v[206:207], v[142:143], 0, s[6:7]
	v_mfma_f32_16x16x32_bf16 v[122:125], v[166:169], v[228:231], v[122:125]
	v_lshl_add_u64 v[212:213], v[144:145], 0, s[6:7]
	v_mfma_f32_16x16x32_bf16 v[118:121], v[170:173], v[228:231], v[118:121]
	v_lshl_add_u64 v[208:209], v[142:143], 0, s[8:9]
	v_mfma_f32_16x16x32_bf16 v[114:117], v[174:177], v[228:231], v[114:117]
	v_lshl_add_u64 v[214:215], v[144:145], 0, s[8:9]
	s_waitcnt lgkmcnt(2)
	v_mfma_f32_16x16x32_bf16 v[110:113], v[162:165], v[232:235], v[110:113]
	v_mfma_f32_16x16x32_bf16 v[106:109], v[166:169], v[232:235], v[106:109]
	v_mfma_f32_16x16x32_bf16 v[102:105], v[170:173], v[232:235], v[102:105]
	v_mfma_f32_16x16x32_bf16 v[98:101], v[174:177], v[232:235], v[98:101]
	s_waitcnt lgkmcnt(1)
	v_mfma_f32_16x16x32_bf16 v[94:97], v[162:165], v[236:239], v[94:97]
	ds_read_b128 v[228:231], v245 offset:8192
	v_mfma_f32_16x16x32_bf16 v[90:93], v[166:169], v[236:239], v[90:93]
	ds_read_b128 v[232:235], v245 offset:10240
	v_mfma_f32_16x16x32_bf16 v[86:89], v[170:173], v[236:239], v[86:89]
	s_mov_b32 m0, s41
	v_mfma_f32_16x16x32_bf16 v[82:85], v[174:177], v[236:239], v[82:85]
	global_load_lds_dwordx4 v[204:205], off
	s_waitcnt lgkmcnt(2)
	v_mfma_f32_16x16x32_bf16 v[78:81], v[162:165], v[240:243], v[78:81]
	s_mov_b32 m0, s45
	v_mfma_f32_16x16x32_bf16 v[74:77], v[166:169], v[240:243], v[74:77]
	global_load_lds_dwordx4 v[210:211], off
	v_mfma_f32_16x16x32_bf16 v[70:73], v[170:173], v[240:243], v[70:73]
	v_mfma_f32_16x16x32_bf16 v[66:69], v[174:177], v[240:243], v[66:69]
	s_waitcnt lgkmcnt(1)
	v_mfma_f32_16x16x32_bf16 v[62:65], v[162:165], v[228:231], v[62:65]
	ds_read_b128 v[236:239], v245 offset:12288
	v_mfma_f32_16x16x32_bf16 v[58:61], v[166:169], v[228:231], v[58:61]
	ds_read_b128 v[240:243], v245 offset:14336
	v_mfma_f32_16x16x32_bf16 v[54:57], v[170:173], v[228:231], v[54:57]
	s_mov_b32 m0, s42
	v_mfma_f32_16x16x32_bf16 v[50:53], v[174:177], v[228:231], v[50:53]
	global_load_lds_dwordx4 v[206:207], off
	s_waitcnt lgkmcnt(2)
	v_mfma_f32_16x16x32_bf16 v[46:49], v[162:165], v[232:235], v[46:49]
	s_mov_b32 m0, s46
	v_mfma_f32_16x16x32_bf16 v[42:45], v[166:169], v[232:235], v[42:45]
	global_load_lds_dwordx4 v[212:213], off
	v_mfma_f32_16x16x32_bf16 v[34:37], v[170:173], v[232:235], v[34:37]
	v_mfma_f32_16x16x32_bf16 v[30:33], v[174:177], v[232:235], v[30:33]
	s_waitcnt lgkmcnt(1)
	v_mfma_f32_16x16x32_bf16 v[26:29], v[162:165], v[236:239], v[26:29]
	ds_read_b128 v[178:181], v246 offset:32768
	v_mfma_f32_16x16x32_bf16 v[22:25], v[166:169], v[236:239], v[22:25]
	ds_read_b128 v[182:185], v246 offset:34816
	v_mfma_f32_16x16x32_bf16 v[18:21], v[170:173], v[236:239], v[18:21]
	ds_read_b128 v[220:223], v246 offset:36864
	v_mfma_f32_16x16x32_bf16 v[14:17], v[174:177], v[236:239], v[14:17]
	ds_read_b128 v[224:227], v246 offset:38912
	s_waitcnt lgkmcnt(4)
	v_mfma_f32_16x16x32_bf16 v[10:13], v[162:165], v[240:243], v[10:13]
	ds_read_b128 v[228:231], v247
	v_mfma_f32_16x16x32_bf16 v[6:9], v[166:169], v[240:243], v[6:9]
	ds_read_b128 v[232:235], v247 offset:2048
	v_mfma_f32_16x16x32_bf16 v[2:5], v[170:173], v[240:243], v[2:5]
	s_mov_b32 m0, s43
	v_mfma_f32_16x16x32_bf16 v[38:41], v[174:177], v[240:243], v[38:41]
	global_load_lds_dwordx4 v[208:209], off
	s_mov_b32 m0, s47
	v_lshl_add_u64 v[142:143], v[142:143], 0, s[10:11]
	global_load_lds_dwordx4 v[214:215], off
	v_lshl_add_u64 v[144:145], v[144:145], 0, s[10:11]
	s_waitcnt lgkmcnt(1)
	v_mfma_f32_16x16x32_bf16 v[126:129], v[178:181], v[228:231], v[126:129]
	ds_read_b128 v[236:239], v247 offset:4096
	v_mfma_f32_16x16x32_bf16 v[122:125], v[182:185], v[228:231], v[122:125]
	ds_read_b128 v[240:243], v247 offset:6144
	v_mfma_f32_16x16x32_bf16 v[118:121], v[220:223], v[228:231], v[118:121]
	v_mfma_f32_16x16x32_bf16 v[114:117], v[224:227], v[228:231], v[114:117]
	s_waitcnt lgkmcnt(2)
	v_mfma_f32_16x16x32_bf16 v[110:113], v[178:181], v[232:235], v[110:113]
	v_mfma_f32_16x16x32_bf16 v[106:109], v[182:185], v[232:235], v[106:109]
	v_mfma_f32_16x16x32_bf16 v[102:105], v[220:223], v[232:235], v[102:105]
	v_mfma_f32_16x16x32_bf16 v[98:101], v[224:227], v[232:235], v[98:101]
	s_waitcnt lgkmcnt(1)
	v_mfma_f32_16x16x32_bf16 v[94:97], v[178:181], v[236:239], v[94:97]
	ds_read_b128 v[228:231], v247 offset:8192
	v_mfma_f32_16x16x32_bf16 v[90:93], v[182:185], v[236:239], v[90:93]
	ds_read_b128 v[232:235], v247 offset:10240
	v_mfma_f32_16x16x32_bf16 v[86:89], v[220:223], v[236:239], v[86:89]
	v_mfma_f32_16x16x32_bf16 v[82:85], v[224:227], v[236:239], v[82:85]
	s_waitcnt lgkmcnt(2)
; DEV unsigned cvt_pk_bf16(float lo, float hi) { const f32x2_t v = {lo, hi}; const bf16x2_t b = __builtin_convertvector(v, bf16x2_t); return __builtin_bit_cast(unsigned, b); }
; #define GLDS_STAGE(st, kt_) do { \
;         _Pragma("unroll") for (int i_ = 0; i_ < FI; ++i_) { \
;             glds16(ap + (size_t)(32 * i_) * lda + (kt_) * 64, l3a + (st) + tid * 16 + i_ * 4096); \
;             glds16(bp + (size_t)(32 * i_) * ldb + (kt_) * 64, l3a + (st) + OPB + tid * 16 + i_ * 4096); } } while (0)
; template <class Epi>
; DEV void gemm256_tile(const bf16_t* __restrict__ A, int lda, const bf16_t* __restrict__ Bt, int ldb, int K, unsigned char* lds, const Epi& epi) {
;     ...
;     for (int kt = 0; kt < nk; ++kt) {
;         const int cur = (kt & 1) * 65536;
;         asm volatile("s_waitcnt vmcnt(0)" ::: "memory");
;         __syncthreads();
;         if (kt + 1 < nk) GLDS_STAGE(cur ^ 65536, kt + 1);
; #pragma unroll
;         for (int kh = 0; kh < 2; ++kh) {
;             bf16x8 bfr[4];
;             const int ch = ((kh * 4 + fq) ^ sw) << 4;
; #pragma unroll
;             for (int i = 0; i < 4; ++i) bfr[i] = *(const bf16x8*)(lds + cur + boff + i * 2048 + ch);
; #pragma unroll
;             for (int mh = 0; mh < 2; ++mh) {
;                 bf16x8 af[4];
; #pragma unroll
;                 for (int i = 0; i < 4; ++i) af[i] = *(const bf16x8*)(lds + cur + aoff + (mh * 4 + i) * 2048 + ch);
; #pragma unroll
;                 for (int mi = 0; mi < 4; ++mi)
; #pragma unroll
;                     for (int ni = 0; ni < 4; ++ni) acc[mh * 4 + mi][ni] = __builtin_amdgcn_mfma_f32_16x16x32_bf16(bfr[ni], af[mi], acc[mh * 4 + mi][ni], 0, 0, 0);
;             }
;         }
;     }
;     ...
;     __syncthreads();
;     if constexpr (Epi::STAGE) {
; #pragma unroll
;         for (int mi = 0; mi < 8; ++mi)
; #pragma unroll
;             for (int ni = 0; ni < 4; ++ni) {
;                 const int row = wr * 128 + mi * 16 + fr, col = wc * 64 + ni * 16 + fq * 4;
;                 const f32x4 v = epi.xform(row, col, acc[mi][ni]);
;                 uint2 w; w.x = cvt_pk_bf16(v[0], v[1]); w.y = cvt_pk_bf16(v[2], v[3]);
;                 *(uint2*)(lds + row * 512 + ((((col >> 3) ^ (row & 31)) << 4) | (((col >> 2) & 1) << 3))) = w;
	v_mfma_f32_16x16x32_bf16 v[78:81], v[178:181], v[240:243], v[78:81]
	v_mfma_f32_16x16x32_bf16 v[74:77], v[182:185], v[240:243], v[74:77]
	v_mfma_f32_16x16x32_bf16 v[70:73], v[220:223], v[240:243], v[70:73]
	v_mfma_f32_16x16x32_bf16 v[66:69], v[224:227], v[240:243], v[66:69]
	s_waitcnt lgkmcnt(1)
	v_mfma_f32_16x16x32_bf16 v[62:65], v[178:181], v[228:231], v[62:65]
	ds_read_b128 v[236:239], v247 offset:12288
	v_mfma_f32_16x16x32_bf16 v[58:61], v[182:185], v[228:231], v[58:61]
	ds_read_b128 v[240:243], v247 offset:14336
	v_mfma_f32_16x16x32_bf16 v[54:57], v[220:223], v[228:231], v[54:57]
	v_mfma_f32_16x16x32_bf16 v[50:53], v[224:227], v[228:231], v[50:53]
	s_waitcnt lgkmcnt(2)
	v_mfma_f32_16x16x32_bf16 v[46:49], v[178:181], v[232:235], v[46:49]
	v_mfma_f32_16x16x32_bf16 v[42:45], v[182:185], v[232:235], v[42:45]
	v_mfma_f32_16x16x32_bf16 v[34:37], v[220:223], v[232:235], v[34:37]
	v_mfma_f32_16x16x32_bf16 v[30:33], v[224:227], v[232:235], v[30:33]
	s_waitcnt lgkmcnt(1)
	v_mfma_f32_16x16x32_bf16 v[26:29], v[178:181], v[236:239], v[26:29]
	v_mfma_f32_16x16x32_bf16 v[22:25], v[182:185], v[236:239], v[22:25]
	v_mfma_f32_16x16x32_bf16 v[18:21], v[220:223], v[236:239], v[18:21]
	v_mfma_f32_16x16x32_bf16 v[14:17], v[224:227], v[236:239], v[14:17]
	s_waitcnt lgkmcnt(0)
	v_mfma_f32_16x16x32_bf16 v[10:13], v[178:181], v[240:243], v[10:13]
	v_mfma_f32_16x16x32_bf16 v[6:9], v[182:185], v[240:243], v[6:9]
	v_mfma_f32_16x16x32_bf16 v[2:5], v[220:223], v[240:243], v[2:5]
	v_mfma_f32_16x16x32_bf16 v[38:41], v[224:227], v[240:243], v[38:41]
	s_cmp_eq_u32 s21, 0x1f0000
	s_cbranch_scc0 .LBB0_1466
	s_setprio 0
	v_or_b32_e32 v184, 0x18000, v155
	v_add_u32_e32 v156, v184, v154
	s_waitcnt vmcnt(0)
	s_barrier
	ds_read_b128 v[142:145], v156
	ds_read_b128 v[162:165], v156 offset:2048
	ds_read_b128 v[166:169], v156 offset:4096
	ds_read_b128 v[170:173], v156 offset:6144
	v_add_u32_e32 v198, 0x10000, v152
	v_add_u32_e32 v178, v198, v154
	ds_read_b128 v[152:155], v178
	s_waitcnt lgkmcnt(0)
	v_mfma_f32_16x16x32_bf16 v[126:129], v[142:145], v[152:155], v[126:129]
	s_sext_i32_i8 s14, s20
	s_lshl_b32 s20, s14, 8
	s_ashr_i32 s21, s20, 31
	v_mfma_f32_16x16x32_bf16 v[122:125], v[162:165], v[152:155], v[122:125]
	v_lshl_add_u64 v[156:157], v[134:135], 0, s[12:13]
	v_lshl_add_u64 v[182:183], v[130:131], 0, s[12:13]
	s_lshl_b64 s[12:13], s[20:21], 1
	v_mfma_f32_16x16x32_bf16 v[118:121], v[166:169], v[152:155], v[118:121]
	v_lshlrev_b32_e32 v148, 3, v148
	v_lshlrev_b32_e32 v150, 9, v150
	v_and_or_b32 v148, v148, 8, v150
	v_mfma_f32_16x16x32_bf16 v[114:117], v[170:173], v[152:155], v[114:117]
	ds_read_b128 v[152:155], v178 offset:2048
	s_waitcnt lgkmcnt(0)
	v_mfma_f32_16x16x32_bf16 v[110:113], v[142:145], v[152:155], v[110:113]
	v_mfma_f32_16x16x32_bf16 v[106:109], v[162:165], v[152:155], v[106:109]
	v_mfma_f32_16x16x32_bf16 v[102:105], v[166:169], v[152:155], v[102:105]
	v_mfma_f32_16x16x32_bf16 v[98:101], v[170:173], v[152:155], v[98:101]
	ds_read_b128 v[152:155], v178 offset:4096
	s_waitcnt lgkmcnt(0)
	v_mfma_f32_16x16x32_bf16 v[94:97], v[142:145], v[152:155], v[94:97]
	v_mfma_f32_16x16x32_bf16 v[90:93], v[162:165], v[152:155], v[90:93]
	v_mfma_f32_16x16x32_bf16 v[86:89], v[166:169], v[152:155], v[86:89]
	v_mfma_f32_16x16x32_bf16 v[82:85], v[170:173], v[152:155], v[82:85]
	ds_read_b128 v[152:155], v178 offset:6144
	s_waitcnt lgkmcnt(0)
	v_mfma_f32_16x16x32_bf16 v[78:81], v[142:145], v[152:155], v[78:81]
	v_mfma_f32_16x16x32_bf16 v[74:77], v[162:165], v[152:155], v[74:77]
	v_mfma_f32_16x16x32_bf16 v[70:73], v[166:169], v[152:155], v[70:73]
	v_mfma_f32_16x16x32_bf16 v[66:69], v[170:173], v[152:155], v[66:69]
	ds_read_b128 v[152:155], v178 offset:8192
	ds_read_b128 v[174:177], v178 offset:10240
	s_waitcnt lgkmcnt(1)
	v_mfma_f32_16x16x32_bf16 v[62:65], v[142:145], v[152:155], v[62:65]
	v_mfma_f32_16x16x32_bf16 v[58:61], v[162:165], v[152:155], v[58:61]
	v_mfma_f32_16x16x32_bf16 v[54:57], v[166:169], v[152:155], v[54:57]
	v_mfma_f32_16x16x32_bf16 v[50:53], v[170:173], v[152:155], v[50:53]
	ds_read_b128 v[152:155], v178 offset:12288
	s_waitcnt lgkmcnt(1)
	v_mfma_f32_16x16x32_bf16 v[46:49], v[142:145], v[174:177], v[46:49]
	v_mfma_f32_16x16x32_bf16 v[42:45], v[162:165], v[174:177], v[42:45]
	v_mfma_f32_16x16x32_bf16 v[34:37], v[166:169], v[174:177], v[34:37]
	v_mfma_f32_16x16x32_bf16 v[30:33], v[170:173], v[174:177], v[30:33]
	ds_read_b128 v[174:177], v178 offset:14336
	s_waitcnt lgkmcnt(1)
	v_mfma_f32_16x16x32_bf16 v[178:181], v[142:145], v[152:155], v[26:29]
	s_nop 2
	v_lshl_add_u64 v[28:29], v[156:157], 0, s[12:13]
	v_add_u32_e32 v157, v184, v151
	v_lshl_add_u64 v[26:27], v[182:183], 0, s[12:13]
	ds_read_b128 v[182:185], v157
	ds_read_b128 v[186:189], v157 offset:2048
	ds_read_b128 v[190:193], v157 offset:4096
	ds_read_b128 v[194:197], v157 offset:6144
	v_add_u32_e32 v151, v198, v151
	v_mfma_f32_16x16x32_bf16 v[22:25], v[162:165], v[152:155], v[22:25]
	v_and_b32_e32 v156, 0xc0, v146
	v_lshl_or_b32 v149, v149, 2, v156
	s_mov_b32 s12, 0
	v_mfma_f32_16x16x32_bf16 v[18:21], v[166:169], v[152:155], v[18:21]
	v_mfma_f32_16x16x32_bf16 v[14:17], v[170:173], v[152:155], v[14:17]
	ds_read_b128 v[152:155], v151
	ds_read_b128 v[198:201], v151 offset:2048
	ds_read_b128 v[202:205], v151 offset:4096
	ds_read_b128 v[206:209], v151 offset:6144
	s_waitcnt lgkmcnt(8)
	v_mfma_f32_16x16x32_bf16 v[10:13], v[142:145], v[174:177], v[10:13]
	ds_read_b128 v[142:145], v151 offset:8192
	ds_read_b128 v[210:213], v151 offset:10240
	ds_read_b128 v[214:217], v151 offset:12288
	ds_read_b128 v[218:221], v151 offset:14336
	s_waitcnt lgkmcnt(0)
	s_barrier
; DEV unsigned cvt_pk_bf16(float lo, float hi) { const f32x2_t v = {lo, hi}; const bf16x2_t b = __builtin_convertvector(v, bf16x2_t); return __builtin_bit_cast(unsigned, b); }
; template <class Epi>
; DEV void gemm256_tile(const bf16_t* __restrict__ A, int lda, const bf16_t* __restrict__ Bt, int ldb, int K, unsigned char* lds, const Epi& epi) {
;     ...
;     __syncthreads();
;     if constexpr (Epi::STAGE) {
; #pragma unroll
;         for (int mi = 0; mi < 8; ++mi)
; #pragma unroll
;             for (int ni = 0; ni < 4; ++ni) {
;                 const int row = wr * 128 + mi * 16 + fr, col = wc * 64 + ni * 16 + fq * 4;
;                 const f32x4 v = epi.xform(row, col, acc[mi][ni]);
;                 uint2 w; w.x = cvt_pk_bf16(v[0], v[1]); w.y = cvt_pk_bf16(v[2], v[3]);
;                 *(uint2*)(lds + row * 512 + ((((col >> 3) ^ (row & 31)) << 4) | (((col >> 2) & 1) << 3))) = w;
;             }
;         __syncthreads();
	v_mfma_f32_16x16x32_bf16 v[2:5], v[166:169], v[174:177], v[2:5]
	v_mfma_f32_16x16x32_bf16 v[126:129], v[182:185], v[152:155], v[126:129]
	v_mfma_f32_16x16x32_bf16 v[114:117], v[194:197], v[152:155], v[114:117]
	v_mfma_f32_16x16x32_bf16 v[102:105], v[190:193], v[198:201], v[102:105]
	s_nop 5
	v_cvt_pk_bf16_f32 v126, v126, v127
	v_cvt_pk_bf16_f32 v127, v128, v129
	v_lshrrev_b32_e32 v128, 3, v149
	v_mfma_f32_16x16x32_bf16 v[34:37], v[190:193], v[210:213], v[34:37]
	v_cvt_pk_bf16_f32 v114, v114, v115
	v_cvt_pk_bf16_f32 v115, v116, v117
	v_or_b32_e32 v117, 16, v147
	v_mfma_f32_16x16x32_bf16 v[2:5], v[190:193], v[218:221], v[2:5]
	v_cvt_pk_bf16_f32 v102, v102, v103
	v_cvt_pk_bf16_f32 v103, v104, v105
	v_bitop3_b32 v104, v128, v117, 4 bitop3:0x36
	v_mfma_f32_16x16x32_bf16 v[38:41], v[170:173], v[174:177], v[38:41]
	v_lshl_add_u32 v104, v104, 4, v148
	v_cvt_pk_bf16_f32 v34, v34, v35
	v_cvt_pk_bf16_f32 v35, v36, v37
	v_mfma_f32_16x16x32_bf16 v[6:9], v[162:165], v[174:177], v[6:9]
	v_cvt_pk_bf16_f32 v2, v2, v3
	v_cvt_pk_bf16_f32 v3, v4, v5
	ds_write2st64_b64 v104, v[34:35], v[2:3] offset0:80 offset1:112
	v_mfma_f32_16x16x32_bf16 v[30:33], v[194:197], v[210:213], v[30:33]
	v_xor_b32_e32 v129, v128, v147
	v_bitop3_b32 v116, v128, v147, 6 bitop3:0x36
	v_lshl_or_b32 v129, v129, 4, v148
	v_mfma_f32_16x16x32_bf16 v[98:101], v[194:197], v[198:201], v[98:101]
	v_lshl_add_u32 v116, v116, 4, v148
	s_nop 2
	v_cvt_pk_bf16_f32 v36, v30, v31
	v_cvt_pk_bf16_f32 v37, v32, v33
	v_mfma_f32_16x16x32_bf16 v[122:125], v[186:189], v[152:155], v[122:125]
	v_mfma_f32_16x16x32_bf16 v[118:121], v[190:193], v[152:155], v[118:121]
	v_cvt_pk_bf16_f32 v98, v98, v99
	v_cvt_pk_bf16_f32 v99, v100, v101
	v_bitop3_b32 v100, v128, v117, 6 bitop3:0x36
	v_mfma_f32_16x16x32_bf16 v[110:113], v[182:185], v[198:201], v[110:113]
	s_nop 2
	v_cvt_pk_bf16_f32 v122, v122, v123
	v_cvt_pk_bf16_f32 v123, v124, v125
	v_bitop3_b32 v124, v128, v147, 2 bitop3:0x36
	v_mfma_f32_16x16x32_bf16 v[106:109], v[186:189], v[198:201], v[106:109]
	v_cvt_pk_bf16_f32 v118, v118, v119
	v_cvt_pk_bf16_f32 v119, v120, v121
	v_bitop3_b32 v120, v128, v147, 4 bitop3:0x36
	v_mfma_f32_16x16x32_bf16 v[2:5], v[194:197], v[218:221], v[38:41]
	v_cvt_pk_bf16_f32 v110, v110, v111
	v_cvt_pk_bf16_f32 v111, v112, v113
	v_bitop3_b32 v112, v128, v147, 16 bitop3:0x1e
	v_mfma_f32_16x16x32_bf16 v[94:97], v[182:185], v[202:205], v[94:97]
	v_cvt_pk_bf16_f32 v106, v106, v107
	v_cvt_pk_bf16_f32 v107, v108, v109
	v_bitop3_b32 v108, v128, v117, 2 bitop3:0x36
	v_mfma_f32_16x16x32_bf16 v[90:93], v[186:189], v[202:205], v[90:93]
	v_lshl_add_u32 v100, v100, 4, v148
	v_cvt_pk_bf16_f32 v2, v2, v3
	v_cvt_pk_bf16_f32 v3, v4, v5
	v_mfma_f32_16x16x32_bf16 v[86:89], v[190:193], v[202:205], v[86:89]
	v_lshl_add_u32 v124, v124, 4, v148
	v_lshl_add_u32 v120, v120, 4, v148
	v_lshl_or_b32 v112, v112, 4, v148
	v_mfma_f32_16x16x32_bf16 v[82:85], v[194:197], v[202:205], v[82:85]
	v_lshl_add_u32 v108, v108, 4, v148
	v_cvt_pk_bf16_f32 v94, v94, v95
	v_cvt_pk_bf16_f32 v95, v96, v97
	v_mfma_f32_16x16x32_bf16 v[78:81], v[182:185], v[206:209], v[78:81]
	v_cvt_pk_bf16_f32 v90, v90, v91
	v_cvt_pk_bf16_f32 v91, v92, v93
	v_cvt_pk_bf16_f32 v86, v86, v87
	v_mfma_f32_16x16x32_bf16 v[74:77], v[186:189], v[206:209], v[74:77]
	v_cvt_pk_bf16_f32 v87, v88, v89
	v_cvt_pk_bf16_f32 v82, v82, v83
	v_cvt_pk_bf16_f32 v83, v84, v85
	v_mfma_f32_16x16x32_bf16 v[70:73], v[190:193], v[206:209], v[70:73]
	v_cvt_pk_bf16_f32 v78, v78, v79
	v_cvt_pk_bf16_f32 v79, v80, v81
	s_nop 1
	v_cvt_pk_bf16_f32 v74, v74, v75
	v_mfma_f32_16x16x32_bf16 v[66:69], v[194:197], v[206:209], v[66:69]
	v_cvt_pk_bf16_f32 v75, v76, v77
	s_nop 0
	v_cvt_pk_bf16_f32 v70, v70, v71
	v_cvt_pk_bf16_f32 v71, v72, v73
	v_mfma_f32_16x16x32_bf16 v[62:65], v[182:185], v[142:145], v[62:65]
	ds_write2st64_b64 v100, v[36:37], v[2:3] offset0:80 offset1:112
	s_nop 1
	v_cvt_pk_bf16_f32 v66, v66, v67
	v_cvt_pk_bf16_f32 v67, v68, v69
	v_mfma_f32_16x16x32_bf16 v[58:61], v[186:189], v[142:145], v[58:61]
	v_and_b32_e32 v2, 0x1f0, v140
	s_nop 0
	v_cvt_pk_bf16_f32 v62, v62, v63
	v_cvt_pk_bf16_f32 v63, v64, v65
	v_mfma_f32_16x16x32_bf16 v[54:57], v[190:193], v[142:145], v[54:57]
	ds_write2st64_b64 v129, v[126:127], v[94:95] offset1:32
	s_nop 1
	v_cvt_pk_bf16_f32 v58, v58, v59
	v_cvt_pk_bf16_f32 v59, v60, v61
	v_mfma_f32_16x16x32_bf16 v[50:53], v[194:197], v[142:145], v[50:53]
	ds_write2st64_b64 v124, v[122:123], v[90:91] offset1:32
	s_nop 0
	v_cvt_pk_bf16_f32 v54, v54, v55
	v_cvt_pk_bf16_f32 v55, v56, v57
	v_mfma_f32_16x16x32_bf16 v[46:49], v[182:185], v[210:213], v[46:49]
	ds_write2st64_b64 v120, v[118:119], v[86:87] offset1:32
	s_nop 1
	v_cvt_pk_bf16_f32 v50, v50, v51
	v_cvt_pk_bf16_f32 v51, v52, v53
	v_mfma_f32_16x16x32_bf16 v[42:45], v[186:189], v[210:213], v[42:45]
	ds_write2st64_b64 v116, v[114:115], v[82:83] offset1:32
	s_nop 0
	v_cvt_pk_bf16_f32 v46, v46, v47
	v_cvt_pk_bf16_f32 v47, v48, v49
	v_mfma_f32_16x16x32_bf16 v[30:33], v[182:185], v[214:217], v[178:181]
	ds_write2st64_b64 v112, v[110:111], v[78:79] offset0:16 offset1:48
	s_nop 1
	v_cvt_pk_bf16_f32 v42, v42, v43
	v_cvt_pk_bf16_f32 v43, v44, v45
	v_mfma_f32_16x16x32_bf16 v[22:25], v[186:189], v[214:217], v[22:25]
	ds_write2st64_b64 v108, v[106:107], v[74:75] offset0:16 offset1:48
	s_nop 0
	v_cvt_pk_bf16_f32 v30, v30, v31
	v_cvt_pk_bf16_f32 v31, v32, v33
	v_mfma_f32_16x16x32_bf16 v[18:21], v[190:193], v[214:217], v[18:21]
	ds_write2st64_b64 v104, v[102:103], v[70:71] offset0:16 offset1:48
	s_nop 1
	v_cvt_pk_bf16_f32 v22, v22, v23
	v_cvt_pk_bf16_f32 v23, v24, v25
	v_mfma_f32_16x16x32_bf16 v[14:17], v[194:197], v[214:217], v[14:17]
	ds_write2st64_b64 v100, v[98:99], v[66:67] offset0:16 offset1:48
	s_nop 0
	v_cvt_pk_bf16_f32 v18, v18, v19
	v_cvt_pk_bf16_f32 v19, v20, v21
	v_mfma_f32_16x16x32_bf16 v[10:13], v[182:185], v[218:221], v[10:13]
	ds_write2st64_b64 v129, v[62:63], v[30:31] offset0:64 offset1:96
	s_nop 1
	v_cvt_pk_bf16_f32 v14, v14, v15
	v_cvt_pk_bf16_f32 v15, v16, v17
	v_mfma_f32_16x16x32_bf16 v[6:9], v[186:189], v[218:221], v[6:9]
	ds_write2st64_b64 v124, v[58:59], v[22:23] offset0:64 offset1:96
	s_nop 0
	v_cvt_pk_bf16_f32 v10, v10, v11
	v_cvt_pk_bf16_f32 v11, v12, v13
	ds_write2st64_b64 v120, v[54:55], v[18:19] offset0:64 offset1:96
	ds_write2st64_b64 v116, v[50:51], v[14:15] offset0:64 offset1:96
	s_nop 1
	v_cvt_pk_bf16_f32 v6, v6, v7
	v_cvt_pk_bf16_f32 v7, v8, v9
	ds_write2st64_b64 v112, v[46:47], v[10:11] offset0:80 offset1:112
	ds_write2st64_b64 v108, v[42:43], v[6:7] offset0:80 offset1:112
	s_waitcnt lgkmcnt(0)
	s_barrier
